# combo16 = combo15 + ds_read2_b64 split into two ds_read_b64 in the own-block and memory attention tiles
# speedup vs baseline: 1.0134x; 1.0010x over previous
; #define LAS __attribute__((address_space(3)))
; #define MFMA32(a, b, c) __builtin_amdgcn_mfma_f32_32x32x16_bf16((a), (b), (c), 0, 0, 0)
; template <bool CAUSAL>
; __device__ __forceinline__ void attn_tile(const LAS unsigned char* Ks, const LAS unsigned char* Vts, const bf16x8 (&qf)[8], int qi, int r32, int hi, f32x16 (&O)[4], float& m2, float& l) {
;     ...
;     for (int hf = 0; hf < 2; ++hf) {
;         f32x16 S[4];
; #pragma unroll
;         for (int s = 0; s < 4; ++s) {
;             f32x16 a;
; #pragma unroll
;             for (int r = 0; r < 16; ++r) a[r] = 0.f;
;             const LAS unsigned char* kp = Ks + (128 * hf + 32 * s + r32) * KS_STRIDE + 16 * hi;
; #pragma unroll
;             for (int d0 = 0; d0 < 8; ++d0) { const bf16x8 kf = *(const LAS bf16x8*)(kp + 32 * d0); a = MFMA32(kf, qf[d0], a); }
;             S[s] = a;
;             __builtin_amdgcn_sched_barrier(0);
.Lown_full:
.LBB0_23:
	s_lshl_b32 s16, s15, 7
	v_or_b32_e32 v64, s16, v166
	v_mad_u32_u24 v176, v64, s86, v128
	ds_read_b128 v[64:67], v176
	v_mov_b32_e32 v182, v68
	s_waitcnt lgkmcnt(0)
	v_mfma_f32_32x32x16_bf16 v[112:127], v[64:67], v[130:133], 0
	ds_read_b128 v[64:67], v176 offset:32
	s_waitcnt lgkmcnt(0)
	v_mfma_f32_32x32x16_bf16 v[112:127], v[64:67], v[134:137], v[112:127]
	ds_read_b128 v[64:67], v176 offset:64
	s_waitcnt lgkmcnt(0)
	v_mfma_f32_32x32x16_bf16 v[112:127], v[64:67], v[138:141], v[112:127]
	ds_read_b128 v[64:67], v176 offset:96
	s_waitcnt lgkmcnt(0)
	v_mfma_f32_32x32x16_bf16 v[112:127], v[64:67], v[142:145], v[112:127]
	ds_read_b128 v[64:67], v176 offset:128
	s_waitcnt lgkmcnt(0)
	v_mfma_f32_32x32x16_bf16 v[112:127], v[64:67], v[146:149], v[112:127]
	ds_read_b128 v[64:67], v176 offset:160
	s_waitcnt lgkmcnt(0)
	v_mfma_f32_32x32x16_bf16 v[112:127], v[64:67], v[150:153], v[112:127]
	ds_read_b128 v[64:67], v176 offset:192
	s_waitcnt lgkmcnt(0)
	v_mfma_f32_32x32x16_bf16 v[112:127], v[64:67], v[154:157], v[112:127]
	ds_read_b128 v[64:67], v176 offset:224
	s_waitcnt lgkmcnt(0)
	v_mfma_f32_32x32x16_bf16 v[112:127], v[64:67], v[158:161], v[112:127]
	ds_read_b128 v[64:67], v176 offset:8704
	s_waitcnt lgkmcnt(0)
	v_mfma_f32_32x32x16_bf16 v[96:111], v[64:67], v[130:133], 0
	ds_read_b128 v[64:67], v176 offset:8736
	s_waitcnt lgkmcnt(0)
	v_mfma_f32_32x32x16_bf16 v[96:111], v[64:67], v[134:137], v[96:111]
	ds_read_b128 v[64:67], v176 offset:8768
	s_waitcnt lgkmcnt(0)
	v_mfma_f32_32x32x16_bf16 v[96:111], v[64:67], v[138:141], v[96:111]
	ds_read_b128 v[64:67], v176 offset:8800
	s_waitcnt lgkmcnt(0)
	v_mfma_f32_32x32x16_bf16 v[96:111], v[64:67], v[142:145], v[96:111]
	ds_read_b128 v[64:67], v176 offset:8832
	s_waitcnt lgkmcnt(0)
	v_mfma_f32_32x32x16_bf16 v[96:111], v[64:67], v[146:149], v[96:111]
	ds_read_b128 v[64:67], v176 offset:8864
	s_waitcnt lgkmcnt(0)
	v_mfma_f32_32x32x16_bf16 v[96:111], v[64:67], v[150:153], v[96:111]
	ds_read_b128 v[64:67], v176 offset:8896
	s_waitcnt lgkmcnt(0)
	v_mfma_f32_32x32x16_bf16 v[96:111], v[64:67], v[154:157], v[96:111]
	ds_read_b128 v[64:67], v176 offset:8928
	s_waitcnt lgkmcnt(0)
	v_mfma_f32_32x32x16_bf16 v[96:111], v[64:67], v[158:161], v[96:111]
	ds_read_b128 v[64:67], v176 offset:17408
	s_waitcnt lgkmcnt(0)
	v_mfma_f32_32x32x16_bf16 v[80:95], v[64:67], v[130:133], 0
	ds_read_b128 v[64:67], v176 offset:17440
	s_waitcnt lgkmcnt(0)
	v_mfma_f32_32x32x16_bf16 v[80:95], v[64:67], v[134:137], v[80:95]
	ds_read_b128 v[64:67], v176 offset:17472
	s_waitcnt lgkmcnt(0)
	v_mfma_f32_32x32x16_bf16 v[80:95], v[64:67], v[138:141], v[80:95]
	ds_read_b128 v[64:67], v176 offset:17504
	s_waitcnt lgkmcnt(0)
	v_mfma_f32_32x32x16_bf16 v[80:95], v[64:67], v[142:145], v[80:95]
	ds_read_b128 v[64:67], v176 offset:17536
	s_waitcnt lgkmcnt(0)
	v_mfma_f32_32x32x16_bf16 v[80:95], v[64:67], v[146:149], v[80:95]
	ds_read_b128 v[64:67], v176 offset:17568
	s_waitcnt lgkmcnt(0)
	v_mfma_f32_32x32x16_bf16 v[80:95], v[64:67], v[150:153], v[80:95]
	ds_read_b128 v[64:67], v176 offset:17600
	s_waitcnt lgkmcnt(0)
	v_mfma_f32_32x32x16_bf16 v[80:95], v[64:67], v[154:157], v[80:95]
	ds_read_b128 v[64:67], v176 offset:17632
	s_waitcnt lgkmcnt(0)
	v_mfma_f32_32x32x16_bf16 v[80:95], v[64:67], v[158:161], v[80:95]
	ds_read_b128 v[64:67], v176 offset:26112
	ds_read_b128 v[172:175], v176 offset:26144
	s_waitcnt lgkmcnt(1)
	v_mfma_f32_32x32x16_bf16 v[64:79], v[64:67], v[130:133], 0
	s_waitcnt lgkmcnt(0)
	v_mfma_f32_32x32x16_bf16 v[64:79], v[172:175], v[134:137], v[64:79]
	ds_read_b128 v[172:175], v176 offset:26176
	s_waitcnt lgkmcnt(0)
	v_mfma_f32_32x32x16_bf16 v[64:79], v[172:175], v[138:141], v[64:79]
	ds_read_b128 v[172:175], v176 offset:26208
	s_waitcnt lgkmcnt(0)
	v_mfma_f32_32x32x16_bf16 v[64:79], v[172:175], v[142:145], v[64:79]
	ds_read_b128 v[172:175], v176 offset:26240
	s_waitcnt lgkmcnt(0)
	v_mfma_f32_32x32x16_bf16 v[64:79], v[172:175], v[146:149], v[64:79]
	ds_read_b128 v[172:175], v176 offset:26272
	s_waitcnt lgkmcnt(0)
	v_mfma_f32_32x32x16_bf16 v[64:79], v[172:175], v[150:153], v[64:79]
	ds_read_b128 v[172:175], v176 offset:26304
	s_waitcnt lgkmcnt(0)
	v_mfma_f32_32x32x16_bf16 v[64:79], v[172:175], v[154:157], v[64:79]
	ds_read_b128 v[172:175], v176 offset:26336
	s_waitcnt lgkmcnt(0)
; __device__ __forceinline__ int crow(int r, int hi) { return (r & 3) + 8 * (r >> 2) + 4 * hi; }
; template <bool CAUSAL>
; __device__ __forceinline__ void attn_tile(const LAS unsigned char* Ks, const LAS unsigned char* Vts, const bf16x8 (&qf)[8], int qi, int r32, int hi, f32x16 (&O)[4], float& m2, float& l) {
;     ...
;         float mx = -1.0e30f;
; #pragma unroll
;         for (int s = 0; s < 4; ++s)
; #pragma unroll
;             for (int r = 0; r < 16; ++r) { float v = S[s][r]; if (CAUSAL) { if (128 * hf + 32 * s + crow(r, hi) > qi) v = -INFINITY; S[s][r] = v; } mx = fmaxf(mx, v); }
	v_mfma_f32_32x32x16_bf16 v[64:79], v[172:175], v[158:161], v[64:79]
	v_or_b32_e32 v174, s16, v168
	v_cmp_le_i32_e32 vcc, v174, v167
	s_nop 1
	v_cndmask_b32_e32 v176, v238, v112, vcc
	v_cmp_lt_i32_e32 vcc, v174, v167
	s_nop 1
	v_cndmask_b32_e32 v183, v238, v113, vcc
	v_or_b32_e32 v113, 2, v174
	v_cmp_le_i32_e32 vcc, v113, v167
	v_or_b32_e32 v113, 3, v174
	v_max3_f32 v112, v176, s69, v183
	v_cndmask_b32_e32 v114, v238, v114, vcc
	v_cmp_le_i32_e32 vcc, v113, v167
	v_or_b32_e32 v113, 8, v174
	s_nop 0
	v_cndmask_b32_e32 v184, v238, v115, vcc
	v_cmp_le_i32_e32 vcc, v113, v167
	v_or_b32_e32 v113, 9, v174
	v_max3_f32 v112, v112, v114, v184
	v_cndmask_b32_e32 v116, v238, v116, vcc
	v_cmp_le_i32_e32 vcc, v113, v167
	v_or_b32_e32 v113, 10, v174
	s_nop 0
	v_cndmask_b32_e32 v185, v238, v117, vcc
	v_cmp_le_i32_e32 vcc, v113, v167
	v_or_b32_e32 v113, 11, v174
	v_max3_f32 v112, v112, v116, v185
	v_cndmask_b32_e32 v186, v238, v118, vcc
	v_cmp_le_i32_e32 vcc, v113, v167
	v_or_b32_e32 v113, 16, v174
	s_nop 0
	v_cndmask_b32_e32 v187, v238, v119, vcc
	v_cmp_le_i32_e32 vcc, v113, v167
	v_or_b32_e32 v113, 17, v174
	v_max3_f32 v112, v112, v186, v187
	v_cndmask_b32_e32 v120, v238, v120, vcc
	v_cmp_le_i32_e32 vcc, v113, v167
	v_or_b32_e32 v113, 18, v174
	s_nop 0
	v_cndmask_b32_e32 v188, v238, v121, vcc
	v_cmp_le_i32_e32 vcc, v113, v167
	v_or_b32_e32 v113, 19, v174
	v_max3_f32 v112, v112, v120, v188
	v_cndmask_b32_e32 v189, v238, v122, vcc
	v_cmp_le_i32_e32 vcc, v113, v167
	v_or_b32_e32 v113, 24, v174
	s_nop 0
	v_cndmask_b32_e32 v123, v238, v123, vcc
	v_cmp_le_i32_e32 vcc, v113, v167
	v_or_b32_e32 v113, 25, v174
	v_max3_f32 v112, v112, v189, v123
	v_cndmask_b32_e32 v190, v238, v124, vcc
	v_cmp_le_i32_e32 vcc, v113, v167
	v_or_b32_e32 v113, 26, v174
	s_nop 0
	v_cndmask_b32_e32 v125, v238, v125, vcc
	v_cmp_le_i32_e32 vcc, v113, v167
	v_or_b32_e32 v113, 27, v174
	v_max3_f32 v112, v112, v190, v125
	v_cndmask_b32_e32 v191, v238, v126, vcc
	v_cmp_le_i32_e32 vcc, v113, v167
	v_or_b32_e32 v113, 32, v174
	s_nop 0
	v_cndmask_b32_e32 v192, v238, v127, vcc
	v_cmp_le_i32_e32 vcc, v113, v167
	v_max3_f32 v112, v112, v191, v192
	s_nop 0
	v_cndmask_b32_e32 v193, v238, v96, vcc
	v_or_b32_e32 v96, 33, v174
	v_cmp_le_i32_e32 vcc, v96, v167
	s_nop 1
	v_cndmask_b32_e32 v97, v238, v97, vcc
	v_max3_f32 v96, v112, v193, v97
	v_or_b32_e32 v112, 34, v174
	v_cmp_le_i32_e32 vcc, v112, v167
	s_nop 1
	v_cndmask_b32_e32 v194, v238, v98, vcc
	v_or_b32_e32 v98, 35, v174
	v_cmp_le_i32_e32 vcc, v98, v167
	v_or_b32_e32 v98, 40, v174
	s_nop 0
	v_cndmask_b32_e32 v195, v238, v99, vcc
	v_cmp_le_i32_e32 vcc, v98, v167
	v_or_b32_e32 v98, 41, v174
	v_or_b32_e32 v99, 51, v174
	v_cndmask_b32_e32 v196, v238, v100, vcc
	v_cmp_le_i32_e32 vcc, v98, v167
	v_or_b32_e32 v98, 42, v174
	v_max3_f32 v96, v96, v194, v195
	v_cndmask_b32_e32 v197, v238, v101, vcc
	v_cmp_le_i32_e32 vcc, v98, v167
	v_or_b32_e32 v98, 43, v174
	v_max3_f32 v96, v96, v196, v197
	v_cndmask_b32_e32 v172, v238, v102, vcc
	v_cmp_le_i32_e32 vcc, v98, v167
	v_or_b32_e32 v98, 48, v174
	s_nop 0
	v_cndmask_b32_e32 v175, v238, v103, vcc
	v_cmp_le_i32_e32 vcc, v98, v167
	v_or_b32_e32 v98, 49, v174
	v_max3_f32 v96, v96, v172, v175
	v_cndmask_b32_e32 v181, v238, v104, vcc
	v_cmp_le_i32_e32 vcc, v98, v167
	v_or_b32_e32 v98, 50, v174
	s_nop 0
	v_cndmask_b32_e32 v180, v238, v105, vcc
	v_cmp_le_i32_e32 vcc, v98, v167
	v_max3_f32 v96, v96, v181, v180
	s_nop 0
	v_cndmask_b32_e32 v98, v238, v106, vcc
	v_cmp_le_i32_e32 vcc, v99, v167
	v_or_b32_e32 v99, 56, v174
	s_nop 0
	v_cndmask_b32_e32 v179, v238, v107, vcc
	v_cmp_le_i32_e32 vcc, v99, v167
	v_or_b32_e32 v99, 57, v174
	v_max3_f32 v96, v96, v98, v179
	v_cndmask_b32_e32 v117, v238, v108, vcc
	v_cmp_le_i32_e32 vcc, v99, v167
	v_or_b32_e32 v99, 58, v174
	s_nop 0
	v_cndmask_b32_e32 v121, v238, v109, vcc
	v_cmp_le_i32_e32 vcc, v99, v167
	v_or_b32_e32 v99, 59, v174
	v_max3_f32 v96, v96, v117, v121
	v_cndmask_b32_e32 v126, v238, v110, vcc
	v_cmp_le_i32_e32 vcc, v99, v167
	v_or_b32_e32 v99, 64, v174
	s_nop 0
	v_cndmask_b32_e32 v173, v238, v111, vcc
	v_cmp_le_i32_e32 vcc, v99, v167
	v_max3_f32 v96, v96, v126, v173
	s_nop 0
	v_cndmask_b32_e32 v178, v238, v80, vcc
	v_or_b32_e32 v80, 0x41, v174
	v_cmp_le_i32_e32 vcc, v80, v167
	s_nop 1
	v_cndmask_b32_e32 v177, v238, v81, vcc
	v_or_b32_e32 v81, 0x42, v174
	v_cmp_le_i32_e32 vcc, v81, v167
	v_or_b32_e32 v81, 0x43, v174
	v_max3_f32 v80, v96, v178, v177
	v_cndmask_b32_e32 v127, v238, v82, vcc
	v_cmp_le_i32_e32 vcc, v81, v167
	v_or_b32_e32 v81, 0x48, v174
	s_nop 0
	v_cndmask_b32_e32 v101, v238, v83, vcc
	v_cmp_le_i32_e32 vcc, v81, v167
	v_or_b32_e32 v81, 0x49, v174
	v_max3_f32 v80, v80, v127, v101
	v_cndmask_b32_e32 v115, v238, v84, vcc
	v_cmp_le_i32_e32 vcc, v81, v167
	v_or_b32_e32 v81, 0x4a, v174
	s_nop 0
	v_cndmask_b32_e32 v118, v238, v85, vcc
	v_cmp_le_i32_e32 vcc, v81, v167
	v_or_b32_e32 v81, 0x4b, v174
	v_max3_f32 v80, v80, v115, v118
	v_cndmask_b32_e32 v122, v238, v86, vcc
	v_cmp_le_i32_e32 vcc, v81, v167
	v_or_b32_e32 v81, 0x50, v174
	s_nop 0
	v_cndmask_b32_e32 v124, v238, v87, vcc
	v_cmp_le_i32_e32 vcc, v81, v167
	v_or_b32_e32 v81, 0x51, v174
	v_max3_f32 v80, v80, v122, v124
	v_cndmask_b32_e32 v86, v238, v88, vcc
	v_cmp_le_i32_e32 vcc, v81, v167
	v_or_b32_e32 v81, 0x52, v174
	s_nop 0
	v_cndmask_b32_e32 v88, v238, v89, vcc
	v_cmp_le_i32_e32 vcc, v81, v167
	v_or_b32_e32 v81, 0x53, v174
	v_max3_f32 v80, v80, v86, v88
	v_cndmask_b32_e32 v119, v238, v90, vcc
	v_cmp_le_i32_e32 vcc, v81, v167
	v_or_b32_e32 v81, 0x58, v174
	s_nop 0
	v_cndmask_b32_e32 v96, v238, v91, vcc
	v_cmp_le_i32_e32 vcc, v81, v167
	v_or_b32_e32 v81, 0x59, v174
	v_max3_f32 v80, v80, v119, v96
; __device__ __forceinline__ int crow(int r, int hi) { return (r & 3) + 8 * (r >> 2) + 4 * hi; }
; template <bool CAUSAL>
; __device__ __forceinline__ void attn_tile(const LAS unsigned char* Ks, const LAS unsigned char* Vts, const bf16x8 (&qf)[8], int qi, int r32, int hi, f32x16 (&O)[4], float& m2, float& l) {
;     ...
;         for (int s = 0; s < 4; ++s)
; #pragma unroll
;             for (int r = 0; r < 16; ++r) { float v = S[s][r]; if (CAUSAL) { if (128 * hf + 32 * s + crow(r, hi) > qi) v = -INFINITY; S[s][r] = v; } mx = fmaxf(mx, v); }
;         mx = fmaxf(mx, __shfl_xor(mx, 32));
;         const float mn = fmaxf(m, mx * c), alpha = __builtin_amdgcn_exp2f(m - mn);
;         m = mn; lsum *= alpha;
; #pragma unroll
;         for (int d = 0; d < 4; ++d)
; #pragma unroll
;             for (int r = 0; r < 16; ++r) O[d][r] *= alpha;
; #pragma unroll
;         for (int s = 0; s < 4; ++s)
; #pragma unroll
;             for (int r = 0; r < 16; ++r) { const float p = __builtin_amdgcn_exp2f(S[s][r] * c - mn); S[s][r] = p; lsum += p; }
	v_cndmask_b32_e32 v112, v238, v92, vcc
	v_cmp_le_i32_e32 vcc, v81, v167
	v_or_b32_e32 v81, 0x5a, v174
	s_nop 0
	v_cndmask_b32_e32 v106, v238, v93, vcc
	v_cmp_le_i32_e32 vcc, v81, v167
	v_or_b32_e32 v81, 0x5b, v174
	v_max3_f32 v80, v80, v112, v106
	v_cndmask_b32_e32 v85, v238, v94, vcc
	v_cmp_le_i32_e32 vcc, v81, v167
	v_or_b32_e32 v81, 0x60, v174
	s_nop 0
	v_cndmask_b32_e32 v84, v238, v95, vcc
	v_cmp_le_i32_e32 vcc, v81, v167
	v_or_b32_e32 v81, 0x61, v174
	v_max3_f32 v80, v80, v85, v84
	v_cndmask_b32_e32 v64, v238, v64, vcc
	v_cmp_le_i32_e32 vcc, v81, v167
	v_or_b32_e32 v81, 0x62, v174
	s_nop 0
	v_cndmask_b32_e32 v65, v238, v65, vcc
	v_cmp_le_i32_e32 vcc, v81, v167
	v_or_b32_e32 v81, 0x63, v174
	v_max3_f32 v80, v80, v64, v65
	v_cndmask_b32_e32 v66, v238, v66, vcc
	v_cmp_le_i32_e32 vcc, v81, v167
	s_nop 1
	v_cndmask_b32_e32 v67, v238, v67, vcc
	v_max3_f32 v82, v80, v66, v67
	v_or_b32_e32 v80, 0x68, v174
	v_cmp_le_i32_e32 vcc, v80, v167
	s_nop 1
	v_cndmask_b32_e32 v80, v238, v68, vcc
	v_or_b32_e32 v68, 0x69, v174
	v_cmp_le_i32_e32 vcc, v68, v167
	s_nop 1
	v_cndmask_b32_e32 v81, v238, v69, vcc
	v_or_b32_e32 v69, 0x6a, v174
	v_cmp_le_i32_e32 vcc, v69, v167
	v_or_b32_e32 v69, 0x6b, v174
	v_max3_f32 v68, v82, v80, v81
	v_cndmask_b32_e32 v82, v238, v70, vcc
	v_cmp_le_i32_e32 vcc, v69, v167
	v_or_b32_e32 v69, 0x70, v174
	s_nop 0
	v_cndmask_b32_e32 v83, v238, v71, vcc
	v_cmp_le_i32_e32 vcc, v69, v167
	v_or_b32_e32 v69, 0x71, v174
	v_max3_f32 v68, v68, v82, v83
	v_cndmask_b32_e32 v99, v238, v72, vcc
	v_cmp_le_i32_e32 vcc, v69, v167
	v_or_b32_e32 v69, 0x72, v174
	s_nop 0
	v_cndmask_b32_e32 v100, v238, v73, vcc
	v_cmp_le_i32_e32 vcc, v69, v167
	v_or_b32_e32 v69, 0x73, v174
	v_max3_f32 v68, v68, v99, v100
	v_cndmask_b32_e32 v102, v238, v74, vcc
	v_cmp_le_i32_e32 vcc, v69, v167
	v_or_b32_e32 v69, 0x78, v174
	s_nop 0
	v_cndmask_b32_e32 v104, v238, v75, vcc
	v_cmp_le_i32_e32 vcc, v69, v167
	v_or_b32_e32 v69, 0x79, v174
	v_max3_f32 v68, v68, v102, v104
	v_cndmask_b32_e32 v107, v238, v76, vcc
	v_cmp_le_i32_e32 vcc, v69, v167
	v_or_b32_e32 v69, 0x7a, v174
	s_nop 0
	v_cndmask_b32_e32 v109, v238, v77, vcc
	v_cmp_le_i32_e32 vcc, v69, v167
	v_or_b32_e32 v69, 0x7b, v174
	v_max3_f32 v68, v68, v107, v109
	v_cndmask_b32_e32 v110, v238, v78, vcc
	v_cmp_le_i32_e32 vcc, v69, v167
	s_nop 1
	v_cndmask_b32_e32 v113, v238, v79, vcc
	v_max3_f32 v68, v68, v110, v113
	ds_bpermute_b32 v69, v169, v68
	s_waitcnt lgkmcnt(0)
	v_max_f32_e32 v69, v69, v69
	v_max_f32_e32 v68, v68, v69
	v_mul_f32_e32 v68, 0x3e0293ee, v68
	v_max_f32_e32 v69, v182, v182
	v_max_f32_e32 v68, v69, v68
	v_sub_f32_e32 v69, v182, v68
	v_exp_f32_e32 v70, v69
	v_fma_f32 v69, v176, s87, -v68
	v_exp_f32_e32 v182, v69
	v_fma_f32 v64, v64, s87, -v68
	v_pk_mul_f32 v[62:63], v[62:63], v[70:71] op_sel_hi:[1,0]
	v_pk_mul_f32 v[60:61], v[60:61], v[70:71] op_sel_hi:[1,0]
	v_pk_mul_f32 v[58:59], v[58:59], v[70:71] op_sel_hi:[1,0]
	v_pk_mul_f32 v[56:57], v[56:57], v[70:71] op_sel_hi:[1,0]
	v_pk_mul_f32 v[54:55], v[54:55], v[70:71] op_sel_hi:[1,0]
	v_pk_mul_f32 v[52:53], v[52:53], v[70:71] op_sel_hi:[1,0]
	v_pk_mul_f32 v[50:51], v[50:51], v[70:71] op_sel_hi:[1,0]
	v_pk_mul_f32 v[48:49], v[48:49], v[70:71] op_sel_hi:[1,0]
	v_pk_mul_f32 v[46:47], v[46:47], v[70:71] op_sel_hi:[1,0]
	v_pk_mul_f32 v[44:45], v[44:45], v[70:71] op_sel_hi:[1,0]
	v_pk_mul_f32 v[42:43], v[42:43], v[70:71] op_sel_hi:[1,0]
	v_pk_mul_f32 v[40:41], v[40:41], v[70:71] op_sel_hi:[1,0]
	v_pk_mul_f32 v[38:39], v[38:39], v[70:71] op_sel_hi:[1,0]
	v_pk_mul_f32 v[36:37], v[36:37], v[70:71] op_sel_hi:[1,0]
	v_pk_mul_f32 v[34:35], v[34:35], v[70:71] op_sel_hi:[1,0]
	v_pk_mul_f32 v[32:33], v[32:33], v[70:71] op_sel_hi:[1,0]
	v_pk_mul_f32 v[30:31], v[30:31], v[70:71] op_sel_hi:[1,0]
	v_pk_mul_f32 v[28:29], v[28:29], v[70:71] op_sel_hi:[1,0]
	v_pk_mul_f32 v[26:27], v[26:27], v[70:71] op_sel_hi:[1,0]
	v_pk_mul_f32 v[24:25], v[24:25], v[70:71] op_sel_hi:[1,0]
	v_pk_mul_f32 v[22:23], v[22:23], v[70:71] op_sel_hi:[1,0]
	v_pk_mul_f32 v[20:21], v[20:21], v[70:71] op_sel_hi:[1,0]
	v_pk_mul_f32 v[18:19], v[18:19], v[70:71] op_sel_hi:[1,0]
	v_pk_mul_f32 v[16:17], v[16:17], v[70:71] op_sel_hi:[1,0]
	v_pk_mul_f32 v[14:15], v[14:15], v[70:71] op_sel_hi:[1,0]
	v_pk_mul_f32 v[12:13], v[12:13], v[70:71] op_sel_hi:[1,0]
	v_pk_mul_f32 v[10:11], v[10:11], v[70:71] op_sel_hi:[1,0]
	v_pk_mul_f32 v[8:9], v[8:9], v[70:71] op_sel_hi:[1,0]
	v_pk_mul_f32 v[6:7], v[6:7], v[70:71] op_sel_hi:[1,0]
	v_pk_mul_f32 v[4:5], v[4:5], v[70:71] op_sel_hi:[1,0]
	v_pk_mul_f32 v[2:3], v[2:3], v[70:71] op_sel_hi:[1,0]
	v_pk_mul_f32 v[0:1], v[0:1], v[70:71] op_sel_hi:[1,0]
	v_fma_f32 v69, v171, v70, v182
	v_fma_f32 v70, v183, s87, -v68
	v_exp_f32_e32 v183, v70
	v_fma_f32 v70, v114, s87, -v68
	v_exp_f32_e32 v198, v70
	v_fma_f32 v70, v184, s87, -v68
	v_exp_f32_e32 v184, v70
	v_fma_f32 v70, v116, s87, -v68
	v_exp_f32_e32 v199, v70
	v_fma_f32 v70, v185, s87, -v68
	v_add_f32_e32 v69, v183, v69
	v_exp_f32_e32 v185, v70
	v_fma_f32 v70, v186, s87, -v68
	v_add_f32_e32 v69, v198, v69
	v_exp_f32_e32 v186, v70
	v_fma_f32 v70, v187, s87, -v68
	v_add_f32_e32 v69, v184, v69
	v_exp_f32_e32 v187, v70
	v_fma_f32 v70, v120, s87, -v68
	v_add_f32_e32 v69, v199, v69
	v_exp_f32_e32 v95, v70
	v_fma_f32 v70, v188, s87, -v68
	v_add_f32_e32 v69, v185, v69
	v_exp_f32_e32 v103, v70
	v_fma_f32 v70, v189, s87, -v68
	v_add_f32_e32 v69, v186, v69
	v_exp_f32_e32 v111, v70
	v_fma_f32 v70, v123, s87, -v68
	v_add_f32_e32 v69, v187, v69
	v_exp_f32_e32 v116, v70
	v_fma_f32 v70, v190, s87, -v68
	v_add_f32_e32 v69, v95, v69
	v_exp_f32_e32 v123, v70
	v_fma_f32 v70, v125, s87, -v68
	v_add_f32_e32 v69, v103, v69
	v_exp_f32_e32 v171, v70
; #define LAS __attribute__((address_space(3)))
; __device__ __forceinline__ unsigned cvtpk(float lo, float hi) { f32x2 v = {lo, hi}; bf16x2_t b = __builtin_convertvector(v, bf16x2_t); return __builtin_bit_cast(unsigned, b); }
; #define MFMA32(a, b, c) __builtin_amdgcn_mfma_f32_32x32x16_bf16((a), (b), (c), 0, 0, 0)
; template <bool CAUSAL>
; __device__ __forceinline__ void attn_tile(const LAS unsigned char* Ks, const LAS unsigned char* Vts, const bf16x8 (&qf)[8], int qi, int r32, int hi, f32x16 (&O)[4], float& m2, float& l) {
;     ...
;             for (int r = 0; r < 16; ++r) { const float p = __builtin_amdgcn_exp2f(S[s][r] * c - mn); S[s][r] = p; lsum += p; }
; #pragma unroll
;         for (int s = 0; s < 4; ++s)
; #pragma unroll
;             for (int j = 0; j < 2; ++j) {
;                 u32x4 pw; pw.x = cvtpk(S[s][8 * j + 0], S[s][8 * j + 1]); pw.y = cvtpk(S[s][8 * j + 2], S[s][8 * j + 3]); pw.z = cvtpk(S[s][8 * j + 4], S[s][8 * j + 5]); pw.w = cvtpk(S[s][8 * j + 6], S[s][8 * j + 7]);
;                 const bf16x8 pf = __builtin_bit_cast(bf16x8, pw);
; #pragma unroll
;                 for (int d = 0; d < 4; ++d) {
;                     const LAS unsigned char* vp = Vts + (32 * d + r32) * VT_STRIDE + (128 * hf + 32 * s + 16 * j + 4 * hi) * 2;
;                     const s16x4 lo = *(const LAS s16x4*)vp, h4 = *(const LAS s16x4*)(vp + 16);
;                     const bf16x8 vf = __builtin_shufflevector(lo, h4, 0, 1, 2, 3, 4, 5, 6, 7);
;                     O[d] = MFMA32(vf, pf, O[d]);
	v_fma_f32 v70, v191, s87, -v68
	v_add_f32_e32 v69, v111, v69
	v_exp_f32_e32 v174, v70
	v_fma_f32 v70, v192, s87, -v68
	v_add_f32_e32 v69, v116, v69
	v_exp_f32_e32 v176, v70
	v_fma_f32 v70, v193, s87, -v68
	v_add_f32_e32 v69, v123, v69
	v_exp_f32_e32 v92, v70
	v_fma_f32 v70, v97, s87, -v68
	v_add_f32_e32 v69, v171, v69
	v_exp_f32_e32 v97, v70
	v_fma_f32 v70, v194, s87, -v68
	v_add_f32_e32 v69, v174, v69
	v_exp_f32_e32 v105, v70
	v_fma_f32 v70, v195, s87, -v68
	v_add_f32_e32 v69, v176, v69
	v_exp_f32_e32 v114, v70
	v_fma_f32 v70, v196, s87, -v68
	v_add_f32_e32 v69, v92, v69
	v_exp_f32_e32 v120, v70
	v_fma_f32 v70, v197, s87, -v68
	v_add_f32_e32 v69, v97, v69
	v_exp_f32_e32 v125, v70
	v_fma_f32 v70, v172, s87, -v68
	v_add_f32_e32 v69, v105, v69
	v_exp_f32_e32 v172, v70
	v_fma_f32 v70, v175, s87, -v68
	v_add_f32_e32 v69, v114, v69
	v_exp_f32_e32 v175, v70
	v_fma_f32 v70, v181, s87, -v68
	v_add_f32_e32 v69, v120, v69
	v_exp_f32_e32 v89, v70
	v_fma_f32 v70, v180, s87, -v68
	v_add_f32_e32 v69, v125, v69
	v_exp_f32_e32 v93, v70
	v_fma_f32 v70, v98, s87, -v68
	v_add_f32_e32 v69, v172, v69
	v_exp_f32_e32 v98, v70
	v_fma_f32 v70, v179, s87, -v68
	v_add_f32_e32 v69, v175, v69
	v_exp_f32_e32 v108, v70
	v_fma_f32 v70, v117, s87, -v68
	v_add_f32_e32 v69, v89, v69
	v_exp_f32_e32 v117, v70
	v_fma_f32 v70, v121, s87, -v68
	v_add_f32_e32 v69, v93, v69
	v_exp_f32_e32 v121, v70
	v_fma_f32 v70, v126, s87, -v68
	v_add_f32_e32 v69, v98, v69
	v_exp_f32_e32 v126, v70
	v_fma_f32 v70, v173, s87, -v68
	v_add_f32_e32 v69, v108, v69
	v_exp_f32_e32 v173, v70
	v_fma_f32 v70, v178, s87, -v68
	v_add_f32_e32 v69, v117, v69
	v_exp_f32_e32 v87, v70
	v_fma_f32 v70, v177, s87, -v68
	v_add_f32_e32 v69, v121, v69
	v_exp_f32_e32 v90, v70
	v_fma_f32 v70, v127, s87, -v68
	v_add_f32_e32 v69, v126, v69
	v_exp_f32_e32 v94, v70
	v_fma_f32 v70, v101, s87, -v68
	v_add_f32_e32 v69, v173, v69
	v_exp_f32_e32 v101, v70
	v_fma_f32 v70, v115, s87, -v68
	v_add_f32_e32 v69, v87, v69
	v_exp_f32_e32 v115, v70
	v_fma_f32 v70, v118, s87, -v68
	v_add_f32_e32 v69, v90, v69
	v_exp_f32_e32 v118, v70
	v_fma_f32 v70, v122, s87, -v68
	v_add_f32_e32 v69, v94, v69
	v_exp_f32_e32 v122, v70
	v_fma_f32 v70, v124, s87, -v68
	v_add_f32_e32 v69, v101, v69
	v_exp_f32_e32 v127, v70
	v_fma_f32 v70, v86, s87, -v68
	v_add_f32_e32 v69, v115, v69
	v_exp_f32_e32 v86, v70
	v_fma_f32 v70, v88, s87, -v68
	v_add_f32_e32 v69, v118, v69
	v_exp_f32_e32 v88, v70
	v_fma_f32 v70, v119, s87, -v68
	v_add_f32_e32 v69, v122, v69
	v_exp_f32_e32 v91, v70
	v_fma_f32 v70, v96, s87, -v68
	v_add_f32_e32 v69, v127, v69
	v_exp_f32_e32 v96, v70
	v_fma_f32 v70, v112, s87, -v68
	v_add_f32_e32 v69, v86, v69
	v_exp_f32_e32 v112, v70
	v_fma_f32 v70, v106, s87, -v68
	v_add_f32_e32 v69, v88, v69
	v_exp_f32_e32 v106, v70
	v_fma_f32 v70, v85, s87, -v68
	v_add_f32_e32 v69, v91, v69
	v_exp_f32_e32 v119, v70
	v_fma_f32 v70, v84, s87, -v68
	v_add_f32_e32 v69, v96, v69
	v_exp_f32_e32 v124, v70
	v_add_f32_e32 v69, v112, v69
	v_add_f32_e32 v69, v106, v69
	v_add_f32_e32 v69, v119, v69
	v_exp_f32_e32 v85, v64
	v_fma_f32 v64, v65, s87, -v68
	v_add_f32_e32 v84, v124, v69
	v_exp_f32_e32 v69, v64
	v_fma_f32 v64, v66, s87, -v68
	v_exp_f32_e32 v70, v64
	v_fma_f32 v64, v67, s87, -v68
	v_exp_f32_e32 v71, v64
	v_fma_f32 v64, v80, s87, -v68
	v_exp_f32_e32 v72, v64
	v_fma_f32 v64, v81, s87, -v68
	v_exp_f32_e32 v73, v64
	v_fma_f32 v64, v82, s87, -v68
	v_exp_f32_e32 v74, v64
	v_fma_f32 v64, v83, s87, -v68
	v_exp_f32_e32 v75, v64
	v_fma_f32 v64, v99, s87, -v68
	v_lshl_add_u32 v99, s15, 8, v170
	ds_read_b64 v[178:179], v99
	ds_read_b64 v[180:181], v99 offset:16
	v_exp_f32_e32 v76, v64
	v_fma_f32 v64, v100, s87, -v68
	v_exp_f32_e32 v77, v64
	v_fma_f32 v64, v102, s87, -v68
	v_exp_f32_e32 v78, v64
	v_fma_f32 v64, v104, s87, -v68
	v_exp_f32_e32 v79, v64
	v_fma_f32 v64, v107, s87, -v68
	v_exp_f32_e32 v80, v64
	v_fma_f32 v64, v109, s87, -v68
	v_exp_f32_e32 v81, v64
	v_fma_f32 v64, v110, s87, -v68
	v_exp_f32_e32 v82, v64
	v_fma_f32 v64, v113, s87, -v68
	v_exp_f32_e32 v83, v64
	v_cvt_pk_bf16_f32 v64, v182, v183
	v_cvt_pk_bf16_f32 v65, v198, v184
	v_cvt_pk_bf16_f32 v66, v199, v185
	v_cvt_pk_bf16_f32 v67, v186, v187
	v_add_u32_e32 v100, 0x4000, v99
	v_add_u32_e32 v102, 0x8000, v99
	s_waitcnt lgkmcnt(0)
	v_mfma_f32_32x32x16_bf16 v[48:63], v[178:181], v[64:67], v[48:63]
	ds_read_b64 v[178:179], v100 offset:512
	ds_read_b64 v[180:181], v100 offset:528
	v_add_u32_e32 v104, 0xc000, v99
	s_waitcnt lgkmcnt(0)
	v_mfma_f32_32x32x16_bf16 v[32:47], v[178:181], v[64:67], v[32:47]
	ds_read_b64 v[178:179], v102 offset:1024
	ds_read_b64 v[180:181], v102 offset:1040
	s_waitcnt lgkmcnt(0)
	v_mfma_f32_32x32x16_bf16 v[16:31], v[178:181], v[64:67], v[16:31]
	ds_read_b64 v[178:179], v104 offset:1536
	ds_read_b64 v[180:181], v104 offset:1552
	s_waitcnt lgkmcnt(0)
	v_mfma_f32_32x32x16_bf16 v[0:15], v[178:181], v[64:67], v[0:15]
	v_cvt_pk_bf16_f32 v67, v174, v176
	ds_read_b64 v[176:177], v99 offset:32
	ds_read_b64 v[178:179], v99 offset:48
	v_cvt_pk_bf16_f32 v64, v95, v103
	v_cvt_pk_bf16_f32 v65, v111, v116
	v_cvt_pk_bf16_f32 v66, v123, v171
	s_waitcnt lgkmcnt(0)
	s_nop 0
	v_mfma_f32_32x32x16_bf16 v[48:63], v[176:179], v[64:67], v[48:63]
	ds_read_b64 v[176:177], v100 offset:544
	ds_read_b64 v[178:179], v100 offset:560
	s_waitcnt lgkmcnt(0)
	v_mfma_f32_32x32x16_bf16 v[32:47], v[176:179], v[64:67], v[32:47]
	ds_read_b64 v[176:177], v102 offset:1056
	ds_read_b64 v[178:179], v102 offset:1072
	s_waitcnt lgkmcnt(0)
	v_mfma_f32_32x32x16_bf16 v[16:31], v[176:179], v[64:67], v[16:31]
	ds_read_b64 v[176:177], v104 offset:1568
	ds_read_b64 v[178:179], v104 offset:1584
	s_waitcnt lgkmcnt(0)
; #define LAS __attribute__((address_space(3)))
; __device__ __forceinline__ unsigned cvtpk(float lo, float hi) { f32x2 v = {lo, hi}; bf16x2_t b = __builtin_convertvector(v, bf16x2_t); return __builtin_bit_cast(unsigned, b); }
; #define MFMA32(a, b, c) __builtin_amdgcn_mfma_f32_32x32x16_bf16((a), (b), (c), 0, 0, 0)
; template <bool CAUSAL>
; __device__ __forceinline__ void attn_tile(const LAS unsigned char* Ks, const LAS unsigned char* Vts, const bf16x8 (&qf)[8], int qi, int r32, int hi, f32x16 (&O)[4], float& m2, float& l) {
;     ...
;         for (int s = 0; s < 4; ++s)
; #pragma unroll
;             for (int j = 0; j < 2; ++j) {
;                 u32x4 pw; pw.x = cvtpk(S[s][8 * j + 0], S[s][8 * j + 1]); pw.y = cvtpk(S[s][8 * j + 2], S[s][8 * j + 3]); pw.z = cvtpk(S[s][8 * j + 4], S[s][8 * j + 5]); pw.w = cvtpk(S[s][8 * j + 6], S[s][8 * j + 7]);
;                 const bf16x8 pf = __builtin_bit_cast(bf16x8, pw);
; #pragma unroll
;                 for (int d = 0; d < 4; ++d) {
;                     const LAS unsigned char* vp = Vts + (32 * d + r32) * VT_STRIDE + (128 * hf + 32 * s + 16 * j + 4 * hi) * 2;
;                     const s16x4 lo = *(const LAS s16x4*)vp, h4 = *(const LAS s16x4*)(vp + 16);
;                     const bf16x8 vf = __builtin_shufflevector(lo, h4, 0, 1, 2, 3, 4, 5, 6, 7);
;                     O[d] = MFMA32(vf, pf, O[d]);
;                 }
;                 __builtin_amdgcn_sched_barrier(0);
;             }
;     }
;     lsum += __shfl_xor(lsum, 32);
; __global__ void __launch_bounds__(512, 2) mk_fwd(Args a) {
;     ...
;                     const int nsel = b < 3 ? b : 3; const size_t pi = ((size_t)h * SEQ + tok) * 3;
;                     float M = m2;
; #pragma unroll 1
;                     for (int t = 0; t < nsel; ++t) M = fmaxf(M, ML[pi + t].x);
	v_mfma_f32_32x32x16_bf16 v[0:15], v[176:179], v[64:67], v[0:15]
	v_cvt_pk_bf16_f32 v67, v172, v175
	ds_read_b64 v[174:175], v99 offset:64
	ds_read_b64 v[176:177], v99 offset:80
	v_cvt_pk_bf16_f32 v64, v92, v97
	v_cvt_pk_bf16_f32 v65, v105, v114
	v_cvt_pk_bf16_f32 v66, v120, v125
	s_waitcnt lgkmcnt(0)
	s_nop 0
	v_mfma_f32_32x32x16_bf16 v[48:63], v[174:177], v[64:67], v[48:63]
	ds_read_b64 v[174:175], v100 offset:576
	ds_read_b64 v[176:177], v100 offset:592
	s_waitcnt lgkmcnt(0)
	v_mfma_f32_32x32x16_bf16 v[32:47], v[174:177], v[64:67], v[32:47]
	ds_read_b64 v[174:175], v102 offset:1088
	ds_read_b64 v[176:177], v102 offset:1104
	s_waitcnt lgkmcnt(0)
	v_mfma_f32_32x32x16_bf16 v[16:31], v[174:177], v[64:67], v[16:31]
	ds_read_b64 v[174:175], v104 offset:1600
	ds_read_b64 v[176:177], v104 offset:1616
	s_waitcnt lgkmcnt(0)
	v_mfma_f32_32x32x16_bf16 v[0:15], v[174:177], v[64:67], v[0:15]
	v_cvt_pk_bf16_f32 v65, v98, v108
	ds_read_b64 v[108:109], v99 offset:96
	ds_read_b64 v[110:111], v99 offset:112
	v_cvt_pk_bf16_f32 v64, v89, v93
	v_cvt_pk_bf16_f32 v66, v117, v121
	v_cvt_pk_bf16_f32 v67, v126, v173
	s_waitcnt lgkmcnt(0)
	s_nop 0
	v_mfma_f32_32x32x16_bf16 v[48:63], v[108:111], v[64:67], v[48:63]
	ds_read_b64 v[108:109], v100 offset:608
	ds_read_b64 v[110:111], v100 offset:624
	s_waitcnt lgkmcnt(0)
	v_mfma_f32_32x32x16_bf16 v[32:47], v[108:111], v[64:67], v[32:47]
	ds_read_b64 v[108:109], v102 offset:1120
	ds_read_b64 v[110:111], v102 offset:1136
	s_waitcnt lgkmcnt(0)
	v_mfma_f32_32x32x16_bf16 v[16:31], v[108:111], v[64:67], v[16:31]
	ds_read_b64 v[108:109], v104 offset:1632
	ds_read_b64 v[110:111], v104 offset:1648
	s_waitcnt lgkmcnt(0)
	v_mfma_f32_32x32x16_bf16 v[0:15], v[108:111], v[64:67], v[0:15]
	v_cvt_pk_bf16_f32 v65, v94, v101
	ds_read_b64 v[92:93], v99 offset:128
	ds_read_b64 v[94:95], v99 offset:144
	v_cvt_pk_bf16_f32 v64, v87, v90
	v_cvt_pk_bf16_f32 v66, v115, v118
	v_cvt_pk_bf16_f32 v67, v122, v127
	s_waitcnt lgkmcnt(0)
	s_nop 0
	v_mfma_f32_32x32x16_bf16 v[48:63], v[92:95], v[64:67], v[48:63]
	ds_read_b64 v[92:93], v100 offset:640
	ds_read_b64 v[94:95], v100 offset:656
	s_waitcnt lgkmcnt(0)
	v_mfma_f32_32x32x16_bf16 v[32:47], v[92:95], v[64:67], v[32:47]
	ds_read_b64 v[92:93], v102 offset:1152
	ds_read_b64 v[94:95], v102 offset:1168
	s_waitcnt lgkmcnt(0)
	v_mfma_f32_32x32x16_bf16 v[16:31], v[92:95], v[64:67], v[16:31]
	ds_read_b64 v[92:93], v104 offset:1664
	ds_read_b64 v[94:95], v104 offset:1680
	s_waitcnt lgkmcnt(0)
	v_mfma_f32_32x32x16_bf16 v[0:15], v[92:95], v[64:67], v[0:15]
	v_cvt_pk_bf16_f32 v64, v86, v88
	ds_read_b64 v[86:87], v99 offset:160
	ds_read_b64 v[88:89], v99 offset:176
	v_cvt_pk_bf16_f32 v65, v91, v96
	v_cvt_pk_bf16_f32 v66, v112, v106
	v_cvt_pk_bf16_f32 v67, v119, v124
	s_waitcnt lgkmcnt(0)
	s_nop 0
	v_mfma_f32_32x32x16_bf16 v[48:63], v[86:89], v[64:67], v[48:63]
	ds_read_b64 v[86:87], v100 offset:672
	ds_read_b64 v[88:89], v100 offset:688
	s_waitcnt lgkmcnt(0)
	v_mfma_f32_32x32x16_bf16 v[32:47], v[86:89], v[64:67], v[32:47]
	ds_read_b64 v[86:87], v102 offset:1184
	ds_read_b64 v[88:89], v102 offset:1200
	s_waitcnt lgkmcnt(0)
	v_mfma_f32_32x32x16_bf16 v[16:31], v[86:89], v[64:67], v[16:31]
	ds_read_b64 v[86:87], v104 offset:1696
	ds_read_b64 v[88:89], v104 offset:1712
	s_waitcnt lgkmcnt(0)
	v_mfma_f32_32x32x16_bf16 v[0:15], v[86:89], v[64:67], v[0:15]
	ds_read_b64 v[64:65], v99 offset:192
	ds_read_b64 v[66:67], v99 offset:208
	v_cvt_pk_bf16_f32 v86, v85, v69
	v_cvt_pk_bf16_f32 v87, v70, v71
	v_cvt_pk_bf16_f32 v88, v72, v73
	v_cvt_pk_bf16_f32 v89, v74, v75
	s_waitcnt lgkmcnt(0)
	s_nop 0
	v_mfma_f32_32x32x16_bf16 v[48:63], v[64:67], v[86:89], v[48:63]
	ds_read_b64 v[64:65], v100 offset:704
	ds_read_b64 v[66:67], v100 offset:720
	s_waitcnt lgkmcnt(0)
	v_mfma_f32_32x32x16_bf16 v[32:47], v[64:67], v[86:89], v[32:47]
	ds_read_b64 v[64:65], v102 offset:1216
	ds_read_b64 v[66:67], v102 offset:1232
	s_waitcnt lgkmcnt(0)
	v_mfma_f32_32x32x16_bf16 v[16:31], v[64:67], v[86:89], v[16:31]
	ds_read_b64 v[64:65], v104 offset:1728
	ds_read_b64 v[66:67], v104 offset:1744
	s_waitcnt lgkmcnt(0)
	v_mfma_f32_32x32x16_bf16 v[0:15], v[64:67], v[86:89], v[0:15]
	ds_read_b64 v[64:65], v99 offset:224
	ds_read_b64 v[66:67], v99 offset:240
	v_cvt_pk_bf16_f32 v86, v76, v77
	v_cvt_pk_bf16_f32 v87, v78, v79
	v_cvt_pk_bf16_f32 v88, v80, v81
	v_cvt_pk_bf16_f32 v89, v82, v83
	s_waitcnt lgkmcnt(0)
	s_nop 0
	v_mfma_f32_32x32x16_bf16 v[48:63], v[64:67], v[86:89], v[48:63]
	ds_read_b64 v[64:65], v100 offset:736
	ds_read_b64 v[66:67], v100 offset:752
	s_waitcnt lgkmcnt(0)
	v_mfma_f32_32x32x16_bf16 v[32:47], v[64:67], v[86:89], v[32:47]
	ds_read_b64 v[64:65], v102 offset:1248
	ds_read_b64 v[66:67], v102 offset:1264
	s_waitcnt lgkmcnt(0)
	v_mfma_f32_32x32x16_bf16 v[16:31], v[64:67], v[86:89], v[16:31]
	ds_read_b64 v[64:65], v104 offset:1760
	ds_read_b64 v[66:67], v104 offset:1776
	s_waitcnt lgkmcnt(0)
	v_mfma_f32_32x32x16_bf16 v[0:15], v[64:67], v[86:89], v[0:15]
	v_add_f32_e32 v64, v85, v84
	v_add_f32_e32 v64, v69, v64
	v_add_f32_e32 v64, v70, v64
	v_add_f32_e32 v64, v71, v64
	v_add_f32_e32 v64, v72, v64
	v_add_f32_e32 v64, v73, v64
	v_add_f32_e32 v64, v74, v64
	v_add_f32_e32 v64, v75, v64
	v_add_f32_e32 v64, v76, v64
	v_add_f32_e32 v64, v77, v64
	v_add_f32_e32 v64, v78, v64
	v_add_f32_e32 v64, v79, v64
	v_add_f32_e32 v64, v80, v64
	v_add_f32_e32 v64, v81, v64
	v_add_f32_e32 v64, v82, v64
	s_mov_b32 s15, 1
	s_and_b64 vcc, exec, s[0:1]
	s_mov_b64 s[0:1], 0
	v_add_f32_e32 v171, v83, v64
	s_cbranch_vccnz .LBB0_23
	ds_bpermute_b32 v66, v169, v171
	s_and_b32 s17, s6, 7
	s_min_i32 s15, s14, 3
	s_cmp_gt_i32 s14, 0
	s_mul_i32 s16, s17, 0x60000
	s_cselect_b64 s[0:1], -1, 0
	s_cmp_lt_i32 s14, 1
	v_mov_b32_e32 v69, v68
	s_cbranch_scc1 .LBB0_27
	s_add_u32 s18, s30, s16
	s_addc_u32 s19, s31, 0
	v_mad_i64_i32 v[64:65], s[18:19], v164, 24, s[18:19]
	s_mov_b32 s14, s15
	v_mov_b32_e32 v69, v68

; #define LAS __attribute__((address_space(3)))
; __device__ __forceinline__ int crow(int r, int hi) { return (r & 3) + 8 * (r >> 2) + 4 * hi; }
; #define MFMA32(a, b, c) __builtin_amdgcn_mfma_f32_32x32x16_bf16((a), (b), (c), 0, 0, 0)
; template <bool CAUSAL>
; __device__ __forceinline__ void attn_tile(const LAS unsigned char* Ks, const LAS unsigned char* Vts, const bf16x8 (&qf)[8], int qi, int r32, int hi, f32x16 (&O)[4], float& m2, float& l) {
;     ...
;     for (int hf = 0; hf < 2; ++hf) {
;         f32x16 S[4];
; #pragma unroll
;         for (int s = 0; s < 4; ++s) {
;             f32x16 a;
; #pragma unroll
;             for (int r = 0; r < 16; ++r) a[r] = 0.f;
;             const LAS unsigned char* kp = Ks + (128 * hf + 32 * s + r32) * KS_STRIDE + 16 * hi;
; #pragma unroll
;             for (int d0 = 0; d0 < 8; ++d0) { const bf16x8 kf = *(const LAS bf16x8*)(kp + 32 * d0); a = MFMA32(kf, qf[d0], a); }
;             S[s] = a;
;             __builtin_amdgcn_sched_barrier(0);
;         }
;         float mx = -1.0e30f;
; #pragma unroll
;         for (int s = 0; s < 4; ++s)
; #pragma unroll
;             for (int r = 0; r < 16; ++r) { float v = S[s][r]; if (CAUSAL) { if (128 * hf + 32 * s + crow(r, hi) > qi) v = -INFINITY; S[s][r] = v; } mx = fmaxf(mx, v); }
;         mx = fmaxf(mx, __shfl_xor(mx, 32));
.LBB0_400:
	v_lshl_or_b32 v64, s25, 7, v165
	v_mad_u32_u24 v174, v64, s86, v128
	ds_read_b128 v[64:67], v174
	s_waitcnt lgkmcnt(0)
	v_mfma_f32_32x32x16_bf16 v[112:127], v[64:67], v[130:133], 0
	ds_read_b128 v[64:67], v174 offset:32
	s_waitcnt lgkmcnt(0)
	v_mfma_f32_32x32x16_bf16 v[112:127], v[64:67], v[134:137], v[112:127]
	ds_read_b128 v[64:67], v174 offset:64
	s_waitcnt lgkmcnt(0)
	v_mfma_f32_32x32x16_bf16 v[112:127], v[64:67], v[138:141], v[112:127]
	ds_read_b128 v[64:67], v174 offset:96
	s_waitcnt lgkmcnt(0)
	v_mfma_f32_32x32x16_bf16 v[112:127], v[64:67], v[142:145], v[112:127]
	ds_read_b128 v[64:67], v174 offset:128
	s_waitcnt lgkmcnt(0)
	v_mfma_f32_32x32x16_bf16 v[112:127], v[64:67], v[146:149], v[112:127]
	ds_read_b128 v[64:67], v174 offset:160
	s_waitcnt lgkmcnt(0)
	v_mfma_f32_32x32x16_bf16 v[112:127], v[64:67], v[150:153], v[112:127]
	ds_read_b128 v[64:67], v174 offset:192
	s_waitcnt lgkmcnt(0)
	v_mfma_f32_32x32x16_bf16 v[112:127], v[64:67], v[154:157], v[112:127]
	ds_read_b128 v[64:67], v174 offset:224
	s_waitcnt lgkmcnt(0)
	v_mfma_f32_32x32x16_bf16 v[112:127], v[64:67], v[158:161], v[112:127]
	ds_read_b128 v[64:67], v174 offset:8704
	s_waitcnt lgkmcnt(0)
	v_mfma_f32_32x32x16_bf16 v[96:111], v[64:67], v[130:133], 0
	ds_read_b128 v[64:67], v174 offset:8736
	s_waitcnt lgkmcnt(0)
	v_mfma_f32_32x32x16_bf16 v[96:111], v[64:67], v[134:137], v[96:111]
	ds_read_b128 v[64:67], v174 offset:8768
	s_waitcnt lgkmcnt(0)
	v_mfma_f32_32x32x16_bf16 v[96:111], v[64:67], v[138:141], v[96:111]
	ds_read_b128 v[64:67], v174 offset:8800
	s_waitcnt lgkmcnt(0)
	v_mfma_f32_32x32x16_bf16 v[96:111], v[64:67], v[142:145], v[96:111]
	ds_read_b128 v[64:67], v174 offset:8832
	s_waitcnt lgkmcnt(0)
	v_mfma_f32_32x32x16_bf16 v[96:111], v[64:67], v[146:149], v[96:111]
	ds_read_b128 v[64:67], v174 offset:8864
	s_waitcnt lgkmcnt(0)
	v_mfma_f32_32x32x16_bf16 v[96:111], v[64:67], v[150:153], v[96:111]
	ds_read_b128 v[64:67], v174 offset:8896
	s_waitcnt lgkmcnt(0)
	v_mfma_f32_32x32x16_bf16 v[96:111], v[64:67], v[154:157], v[96:111]
	ds_read_b128 v[64:67], v174 offset:8928
	s_waitcnt lgkmcnt(0)
	v_mfma_f32_32x32x16_bf16 v[96:111], v[64:67], v[158:161], v[96:111]
	ds_read_b128 v[64:67], v174 offset:17408
	ds_read_b128 v[80:83], v174 offset:17440
	s_waitcnt lgkmcnt(1)
	v_mfma_f32_32x32x16_bf16 v[64:79], v[64:67], v[130:133], 0
	s_waitcnt lgkmcnt(0)
	v_mfma_f32_32x32x16_bf16 v[64:79], v[80:83], v[134:137], v[64:79]
	ds_read_b128 v[80:83], v174 offset:17472
	s_waitcnt lgkmcnt(0)
	v_mfma_f32_32x32x16_bf16 v[64:79], v[80:83], v[138:141], v[64:79]
	ds_read_b128 v[80:83], v174 offset:17504
	s_waitcnt lgkmcnt(0)
	v_mfma_f32_32x32x16_bf16 v[64:79], v[80:83], v[142:145], v[64:79]
	ds_read_b128 v[80:83], v174 offset:17536
	s_waitcnt lgkmcnt(0)
	v_mfma_f32_32x32x16_bf16 v[64:79], v[80:83], v[146:149], v[64:79]
	ds_read_b128 v[80:83], v174 offset:17568
	s_waitcnt lgkmcnt(0)
	v_mfma_f32_32x32x16_bf16 v[64:79], v[80:83], v[150:153], v[64:79]
	ds_read_b128 v[80:83], v174 offset:17600
	s_waitcnt lgkmcnt(0)
	v_mfma_f32_32x32x16_bf16 v[64:79], v[80:83], v[154:157], v[64:79]
	ds_read_b128 v[80:83], v174 offset:17632
	s_waitcnt lgkmcnt(0)
	v_mfma_f32_32x32x16_bf16 v[64:79], v[80:83], v[158:161], v[64:79]
	ds_read_b128 v[80:83], v174 offset:26112
	ds_read_b128 v[170:173], v174 offset:26144
	s_waitcnt lgkmcnt(1)
	v_mfma_f32_32x32x16_bf16 v[80:95], v[80:83], v[130:133], 0
	s_waitcnt lgkmcnt(0)
	v_mfma_f32_32x32x16_bf16 v[80:95], v[170:173], v[134:137], v[80:95]
	ds_read_b128 v[170:173], v174 offset:26176
	s_waitcnt lgkmcnt(0)
	v_mfma_f32_32x32x16_bf16 v[80:95], v[170:173], v[138:141], v[80:95]
	ds_read_b128 v[170:173], v174 offset:26208
	s_waitcnt lgkmcnt(0)
	v_mfma_f32_32x32x16_bf16 v[80:95], v[170:173], v[142:145], v[80:95]
	ds_read_b128 v[170:173], v174 offset:26240
	s_waitcnt lgkmcnt(0)
	v_mfma_f32_32x32x16_bf16 v[80:95], v[170:173], v[146:149], v[80:95]
	ds_read_b128 v[170:173], v174 offset:26272
	s_waitcnt lgkmcnt(0)
	v_mfma_f32_32x32x16_bf16 v[80:95], v[170:173], v[150:153], v[80:95]
	ds_read_b128 v[170:173], v174 offset:26304
	s_waitcnt lgkmcnt(0)
	v_mfma_f32_32x32x16_bf16 v[80:95], v[170:173], v[154:157], v[80:95]
	ds_read_b128 v[170:173], v174 offset:26336
	s_waitcnt lgkmcnt(0)
	v_mfma_f32_32x32x16_bf16 v[80:95], v[170:173], v[158:161], v[80:95]
	v_max3_f32 v170, v112, s69, v113
	v_max3_f32 v170, v170, v114, v115
	v_max3_f32 v170, v170, v116, v117
	v_max3_f32 v170, v170, v118, v119
	v_max3_f32 v170, v170, v120, v121
	v_max3_f32 v170, v170, v122, v123
	v_max3_f32 v170, v170, v124, v125
	v_max3_f32 v170, v170, v126, v127
	v_max3_f32 v170, v170, v96, v97
	v_max3_f32 v170, v170, v98, v99
	v_max3_f32 v170, v170, v100, v101
	v_max3_f32 v170, v170, v102, v103
	v_max3_f32 v170, v170, v104, v105
	v_max3_f32 v170, v170, v106, v107
	v_max3_f32 v170, v170, v108, v109
	v_max3_f32 v170, v170, v110, v111
	v_max3_f32 v170, v170, v64, v65
	v_max3_f32 v170, v170, v66, v67
	v_max3_f32 v170, v170, v68, v69
	v_max3_f32 v170, v170, v70, v71
	v_max3_f32 v170, v170, v72, v73
	v_max3_f32 v170, v170, v74, v75
	v_max3_f32 v170, v170, v76, v77
	v_max3_f32 v170, v170, v78, v79
	v_max3_f32 v170, v170, v80, v81
	v_max3_f32 v170, v170, v82, v83
	v_max3_f32 v170, v170, v84, v85
	v_max3_f32 v170, v170, v86, v87
	v_max3_f32 v170, v170, v88, v89
	v_max3_f32 v170, v170, v90, v91
	v_max3_f32 v170, v170, v92, v93
	v_max3_f32 v170, v170, v94, v95
	ds_bpermute_b32 v171, v167, v170
	s_waitcnt lgkmcnt(0)
; template <bool CAUSAL>
; __device__ __forceinline__ void attn_tile(const LAS unsigned char* Ks, const LAS unsigned char* Vts, const bf16x8 (&qf)[8], int qi, int r32, int hi, f32x16 (&O)[4], float& m2, float& l) {
;     ...
;         mx = fmaxf(mx, __shfl_xor(mx, 32));
;         const float mn = fmaxf(m, mx * c), alpha = __builtin_amdgcn_exp2f(m - mn);
;         m = mn; lsum *= alpha;
; #pragma unroll
;         for (int d = 0; d < 4; ++d)
; #pragma unroll
;             for (int r = 0; r < 16; ++r) O[d][r] *= alpha;
; #pragma unroll
;         for (int s = 0; s < 4; ++s)
; #pragma unroll
;             for (int r = 0; r < 16; ++r) { const float p = __builtin_amdgcn_exp2f(S[s][r] * c - mn); S[s][r] = p; lsum += p; }
	v_max_f32_e32 v171, v171, v171
	v_max_f32_e32 v170, v170, v171
	v_mul_f32_e32 v170, 0x3e0293ee, v170
	v_max_f32_e32 v171, v169, v169
	v_max_f32_e32 v170, v171, v170
	v_sub_f32_e32 v169, v169, v170
	v_fma_f32 v112, v112, s87, -v170
	v_exp_f32_e32 v172, v169
	v_exp_f32_e32 v179, v112
	v_fma_f32 v113, v113, s87, -v170
	v_exp_f32_e32 v180, v113
	v_fma_f32 v113, v114, s87, -v170
	v_exp_f32_e32 v181, v113
	v_fma_f32 v113, v115, s87, -v170
	v_exp_f32_e32 v182, v113
	v_fma_f32 v113, v116, s87, -v170
	v_fma_f32 v112, v166, v172, v179
	v_exp_f32_e32 v183, v113
	v_fma_f32 v113, v117, s87, -v170
	v_add_f32_e32 v112, v180, v112
	v_exp_f32_e32 v184, v113
	v_fma_f32 v113, v118, s87, -v170
	v_add_f32_e32 v112, v181, v112
	v_exp_f32_e32 v185, v113
	v_fma_f32 v113, v119, s87, -v170
	v_add_f32_e32 v112, v182, v112
	v_exp_f32_e32 v186, v113
	v_fma_f32 v113, v120, s87, -v170
	v_add_f32_e32 v112, v183, v112
	v_exp_f32_e32 v113, v113
	v_fma_f32 v114, v121, s87, -v170
	v_add_f32_e32 v112, v184, v112
	v_exp_f32_e32 v116, v114
	v_fma_f32 v114, v122, s87, -v170
	v_add_f32_e32 v112, v185, v112
	v_exp_f32_e32 v119, v114
	v_fma_f32 v114, v123, s87, -v170
	v_add_f32_e32 v112, v186, v112
	v_exp_f32_e32 v121, v114
	v_fma_f32 v114, v124, s87, -v170
	v_add_f32_e32 v112, v113, v112
	v_exp_f32_e32 v166, v114
	v_fma_f32 v114, v125, s87, -v170
	v_pk_mul_f32 v[14:15], v[14:15], v[172:173] op_sel_hi:[1,0]
	v_pk_mul_f32 v[12:13], v[12:13], v[172:173] op_sel_hi:[1,0]
	v_pk_mul_f32 v[10:11], v[10:11], v[172:173] op_sel_hi:[1,0]
	v_pk_mul_f32 v[8:9], v[8:9], v[172:173] op_sel_hi:[1,0]
	v_pk_mul_f32 v[6:7], v[6:7], v[172:173] op_sel_hi:[1,0]
	v_pk_mul_f32 v[4:5], v[4:5], v[172:173] op_sel_hi:[1,0]
	v_pk_mul_f32 v[2:3], v[2:3], v[172:173] op_sel_hi:[1,0]
	v_pk_mul_f32 v[0:1], v[0:1], v[172:173] op_sel_hi:[1,0]
	v_pk_mul_f32 v[30:31], v[30:31], v[172:173] op_sel_hi:[1,0]
	v_pk_mul_f32 v[28:29], v[28:29], v[172:173] op_sel_hi:[1,0]
	v_pk_mul_f32 v[26:27], v[26:27], v[172:173] op_sel_hi:[1,0]
	v_pk_mul_f32 v[24:25], v[24:25], v[172:173] op_sel_hi:[1,0]
	v_pk_mul_f32 v[22:23], v[22:23], v[172:173] op_sel_hi:[1,0]
	v_pk_mul_f32 v[20:21], v[20:21], v[172:173] op_sel_hi:[1,0]
	v_pk_mul_f32 v[18:19], v[18:19], v[172:173] op_sel_hi:[1,0]
	v_pk_mul_f32 v[16:17], v[16:17], v[172:173] op_sel_hi:[1,0]
	v_pk_mul_f32 v[46:47], v[46:47], v[172:173] op_sel_hi:[1,0]
	v_pk_mul_f32 v[44:45], v[44:45], v[172:173] op_sel_hi:[1,0]
	v_pk_mul_f32 v[42:43], v[42:43], v[172:173] op_sel_hi:[1,0]
	v_pk_mul_f32 v[40:41], v[40:41], v[172:173] op_sel_hi:[1,0]
	v_pk_mul_f32 v[38:39], v[38:39], v[172:173] op_sel_hi:[1,0]
	v_pk_mul_f32 v[36:37], v[36:37], v[172:173] op_sel_hi:[1,0]
	v_pk_mul_f32 v[34:35], v[34:35], v[172:173] op_sel_hi:[1,0]
	v_pk_mul_f32 v[32:33], v[32:33], v[172:173] op_sel_hi:[1,0]
	v_pk_mul_f32 v[62:63], v[62:63], v[172:173] op_sel_hi:[1,0]
	v_pk_mul_f32 v[60:61], v[60:61], v[172:173] op_sel_hi:[1,0]
	v_pk_mul_f32 v[58:59], v[58:59], v[172:173] op_sel_hi:[1,0]
	v_pk_mul_f32 v[56:57], v[56:57], v[172:173] op_sel_hi:[1,0]
	v_pk_mul_f32 v[54:55], v[54:55], v[172:173] op_sel_hi:[1,0]
	v_pk_mul_f32 v[52:53], v[52:53], v[172:173] op_sel_hi:[1,0]
	v_pk_mul_f32 v[50:51], v[50:51], v[172:173] op_sel_hi:[1,0]
	v_pk_mul_f32 v[48:49], v[48:49], v[172:173] op_sel_hi:[1,0]
	v_add_f32_e32 v112, v116, v112
	v_exp_f32_e32 v173, v114
	v_fma_f32 v114, v126, s87, -v170
	v_add_f32_e32 v112, v119, v112
	v_exp_f32_e32 v176, v114
	v_fma_f32 v114, v127, s87, -v170
	v_add_f32_e32 v112, v121, v112
	v_exp_f32_e32 v178, v114
	v_add_f32_e32 v112, v166, v112
	v_add_f32_e32 v112, v173, v112
	v_add_f32_e32 v112, v176, v112
	v_fma_f32 v96, v96, s87, -v170
	v_add_f32_e32 v114, v178, v112
	v_exp_f32_e32 v112, v96
	v_fma_f32 v97, v97, s87, -v170
	v_fma_f32 v64, v64, s87, -v170
	v_fma_f32 v65, v65, s87, -v170
	v_add_f32_e32 v96, v112, v114
	v_exp_f32_e32 v114, v97
	v_fma_f32 v97, v98, s87, -v170
	v_exp_f32_e32 v117, v97
	v_fma_f32 v97, v99, s87, -v170
	v_exp_f32_e32 v120, v97
	v_fma_f32 v97, v100, s87, -v170
	v_exp_f32_e32 v124, v97
	v_fma_f32 v97, v101, s87, -v170
	v_add_f32_e32 v96, v114, v96
	v_exp_f32_e32 v169, v97
	v_fma_f32 v97, v102, s87, -v170
	v_add_f32_e32 v96, v117, v96
	v_exp_f32_e32 v174, v97
	v_fma_f32 v97, v103, s87, -v170
	v_add_f32_e32 v96, v120, v96
	v_exp_f32_e32 v177, v97
	v_fma_f32 v97, v104, s87, -v170
	v_add_f32_e32 v96, v124, v96
	v_exp_f32_e32 v101, v97
	v_fma_f32 v97, v105, s87, -v170
	v_add_f32_e32 v96, v169, v96
	v_exp_f32_e32 v104, v97
	v_fma_f32 v97, v106, s87, -v170
	v_add_f32_e32 v96, v174, v96
	v_exp_f32_e32 v115, v97
	v_fma_f32 v97, v107, s87, -v170
	v_add_f32_e32 v96, v177, v96
	v_exp_f32_e32 v118, v97
	v_fma_f32 v97, v108, s87, -v170
	v_add_f32_e32 v96, v101, v96
	v_exp_f32_e32 v122, v97
	v_fma_f32 v97, v109, s87, -v170
	v_add_f32_e32 v96, v104, v96
	v_exp_f32_e32 v125, v97
	v_fma_f32 v97, v110, s87, -v170
	v_add_f32_e32 v96, v115, v96
	v_exp_f32_e32 v171, v97
	v_fma_f32 v97, v111, s87, -v170
	v_add_f32_e32 v96, v118, v96
	v_exp_f32_e32 v175, v97
	v_add_f32_e32 v96, v122, v96
	v_exp_f32_e32 v99, v64
	v_add_f32_e32 v96, v125, v96
	v_exp_f32_e32 v102, v65
	v_fma_f32 v65, v66, s87, -v170
	v_add_f32_e32 v96, v171, v96
	v_exp_f32_e32 v105, v65
	v_fma_f32 v65, v67, s87, -v170
	v_add_f32_e32 v96, v175, v96
	v_exp_f32_e32 v107, v65
	v_fma_f32 v65, v68, s87, -v170
	v_add_f32_e32 v64, v99, v96
	v_exp_f32_e32 v109, v65
	v_fma_f32 v65, v69, s87, -v170
	v_add_f32_e32 v64, v102, v64
	v_exp_f32_e32 v111, v65
	v_fma_f32 v65, v70, s87, -v170
	v_add_f32_e32 v64, v105, v64
	v_exp_f32_e32 v126, v65
	v_fma_f32 v65, v71, s87, -v170
	v_add_f32_e32 v64, v107, v64
	v_exp_f32_e32 v172, v65
	v_fma_f32 v65, v72, s87, -v170
; #define LAS __attribute__((address_space(3)))
; __device__ __forceinline__ unsigned cvtpk(float lo, float hi) { f32x2 v = {lo, hi}; bf16x2_t b = __builtin_convertvector(v, bf16x2_t); return __builtin_bit_cast(unsigned, b); }
; #define MFMA32(a, b, c) __builtin_amdgcn_mfma_f32_32x32x16_bf16((a), (b), (c), 0, 0, 0)
; template <bool CAUSAL>
; __device__ __forceinline__ void attn_tile(const LAS unsigned char* Ks, const LAS unsigned char* Vts, const bf16x8 (&qf)[8], int qi, int r32, int hi, f32x16 (&O)[4], float& m2, float& l) {
;     ...
;         for (int s = 0; s < 4; ++s)
; #pragma unroll
;             for (int r = 0; r < 16; ++r) { const float p = __builtin_amdgcn_exp2f(S[s][r] * c - mn); S[s][r] = p; lsum += p; }
; #pragma unroll
;         for (int s = 0; s < 4; ++s)
; #pragma unroll
;             for (int j = 0; j < 2; ++j) {
;                 u32x4 pw; pw.x = cvtpk(S[s][8 * j + 0], S[s][8 * j + 1]); pw.y = cvtpk(S[s][8 * j + 2], S[s][8 * j + 3]); pw.z = cvtpk(S[s][8 * j + 4], S[s][8 * j + 5]); pw.w = cvtpk(S[s][8 * j + 6], S[s][8 * j + 7]);
;                 const bf16x8 pf = __builtin_bit_cast(bf16x8, pw);
; #pragma unroll
;                 for (int d = 0; d < 4; ++d) {
;                     const LAS unsigned char* vp = Vts + (32 * d + r32) * VT_STRIDE + (128 * hf + 32 * s + 16 * j + 4 * hi) * 2;
;                     const s16x4 lo = *(const LAS s16x4*)vp, h4 = *(const LAS s16x4*)(vp + 16);
;                     const bf16x8 vf = __builtin_shufflevector(lo, h4, 0, 1, 2, 3, 4, 5, 6, 7);
;                     O[d] = MFMA32(vf, pf, O[d]);
;                 }
	v_add_f32_e32 v64, v109, v64
	v_exp_f32_e32 v98, v65
	v_fma_f32 v65, v73, s87, -v170
	v_add_f32_e32 v64, v111, v64
	v_exp_f32_e32 v100, v65
	v_fma_f32 v65, v74, s87, -v170
	v_add_f32_e32 v64, v126, v64
	v_exp_f32_e32 v103, v65
	v_fma_f32 v65, v75, s87, -v170
	v_add_f32_e32 v64, v172, v64
	v_exp_f32_e32 v106, v65
	v_fma_f32 v65, v76, s87, -v170
	v_add_f32_e32 v64, v98, v64
	v_exp_f32_e32 v108, v65
	v_fma_f32 v65, v77, s87, -v170
	v_add_f32_e32 v64, v100, v64
	v_exp_f32_e32 v110, v65
	v_fma_f32 v65, v78, s87, -v170
	v_add_f32_e32 v64, v103, v64
	v_exp_f32_e32 v123, v65
	v_fma_f32 v65, v79, s87, -v170
	v_add_f32_e32 v64, v106, v64
	v_exp_f32_e32 v127, v65
	v_add_f32_e32 v64, v108, v64
	v_add_f32_e32 v64, v110, v64
	v_add_f32_e32 v64, v123, v64
	v_add_f32_e32 v96, v127, v64
	v_fma_f32 v64, v80, s87, -v170
	v_exp_f32_e32 v97, v64
	v_fma_f32 v64, v81, s87, -v170
	v_exp_f32_e32 v68, v64
	v_fma_f32 v64, v82, s87, -v170
	v_exp_f32_e32 v69, v64
	v_fma_f32 v64, v83, s87, -v170
	v_exp_f32_e32 v70, v64
	v_fma_f32 v64, v84, s87, -v170
	v_exp_f32_e32 v71, v64
	v_fma_f32 v64, v85, s87, -v170
	v_exp_f32_e32 v72, v64
	v_fma_f32 v64, v86, s87, -v170
	v_exp_f32_e32 v73, v64
	v_fma_f32 v64, v87, s87, -v170
	v_lshl_add_u32 v83, s25, 8, v168
	v_exp_f32_e32 v74, v64
	v_fma_f32 v64, v88, s87, -v170
	ds_read_b64 v[84:85], v83
	ds_read_b64 v[86:87], v83 offset:16
	v_exp_f32_e32 v75, v64
	v_fma_f32 v64, v89, s87, -v170
	v_exp_f32_e32 v76, v64
	v_fma_f32 v64, v90, s87, -v170
	v_exp_f32_e32 v77, v64
	v_fma_f32 v64, v91, s87, -v170
	v_exp_f32_e32 v78, v64
	v_fma_f32 v64, v92, s87, -v170
	v_exp_f32_e32 v79, v64
	v_fma_f32 v64, v93, s87, -v170
	v_exp_f32_e32 v80, v64
	v_fma_f32 v64, v94, s87, -v170
	v_exp_f32_e32 v81, v64
	v_fma_f32 v64, v95, s87, -v170
	v_exp_f32_e32 v82, v64
	v_cvt_pk_bf16_f32 v64, v179, v180
	v_cvt_pk_bf16_f32 v65, v181, v182
	v_cvt_pk_bf16_f32 v66, v183, v184
	v_cvt_pk_bf16_f32 v67, v185, v186
	s_waitcnt lgkmcnt(0)
	s_nop 0
	v_mfma_f32_32x32x16_bf16 v[0:15], v[84:87], v[64:67], v[0:15]
	v_add_u32_e32 v84, 0x4000, v83
	ds_read_b64 v[86:87], v84 offset:512
	ds_read_b64 v[88:89], v84 offset:528
	v_add_u32_e32 v85, 0x8000, v83
	s_waitcnt lgkmcnt(0)
	v_mfma_f32_32x32x16_bf16 v[16:31], v[86:89], v[64:67], v[16:31]
	ds_read_b64 v[86:87], v85 offset:1024
	ds_read_b64 v[88:89], v85 offset:1040
	s_waitcnt lgkmcnt(0)
	v_mfma_f32_32x32x16_bf16 v[32:47], v[86:89], v[64:67], v[32:47]
	v_add_u32_e32 v86, 0xc000, v83
	ds_read_b64 v[88:89], v86 offset:1536
	ds_read_b64 v[90:91], v86 offset:1552
	s_waitcnt lgkmcnt(0)
	v_mfma_f32_32x32x16_bf16 v[48:63], v[88:91], v[64:67], v[48:63]
	ds_read_b64 v[88:89], v83 offset:32
	ds_read_b64 v[90:91], v83 offset:48
	v_cvt_pk_bf16_f32 v64, v113, v116
	v_cvt_pk_bf16_f32 v65, v119, v121
	v_cvt_pk_bf16_f32 v66, v166, v173
	v_cvt_pk_bf16_f32 v67, v176, v178
	s_waitcnt lgkmcnt(0)
	s_nop 0
	v_mfma_f32_32x32x16_bf16 v[0:15], v[88:91], v[64:67], v[0:15]
	ds_read_b64 v[88:89], v84 offset:544
	ds_read_b64 v[90:91], v84 offset:560
	s_waitcnt lgkmcnt(0)
	v_mfma_f32_32x32x16_bf16 v[16:31], v[88:91], v[64:67], v[16:31]
	ds_read_b64 v[88:89], v85 offset:1056
	ds_read_b64 v[90:91], v85 offset:1072
	s_waitcnt lgkmcnt(0)
	v_mfma_f32_32x32x16_bf16 v[32:47], v[88:91], v[64:67], v[32:47]
	ds_read_b64 v[88:89], v86 offset:1568
	ds_read_b64 v[90:91], v86 offset:1584
	s_waitcnt lgkmcnt(0)
	v_mfma_f32_32x32x16_bf16 v[48:63], v[88:91], v[64:67], v[48:63]
	ds_read_b64 v[88:89], v83 offset:64
	ds_read_b64 v[90:91], v83 offset:80
	v_cvt_pk_bf16_f32 v64, v112, v114
	v_cvt_pk_bf16_f32 v65, v117, v120
	v_cvt_pk_bf16_f32 v66, v124, v169
	v_cvt_pk_bf16_f32 v67, v174, v177
	s_waitcnt lgkmcnt(0)
	s_nop 0
	v_mfma_f32_32x32x16_bf16 v[0:15], v[88:91], v[64:67], v[0:15]
	ds_read_b64 v[88:89], v84 offset:576
	ds_read_b64 v[90:91], v84 offset:592
	s_waitcnt lgkmcnt(0)
	v_mfma_f32_32x32x16_bf16 v[16:31], v[88:91], v[64:67], v[16:31]
	ds_read_b64 v[88:89], v85 offset:1088
	ds_read_b64 v[90:91], v85 offset:1104
	s_waitcnt lgkmcnt(0)
	v_mfma_f32_32x32x16_bf16 v[32:47], v[88:91], v[64:67], v[32:47]
	ds_read_b64 v[88:89], v86 offset:1600
	ds_read_b64 v[90:91], v86 offset:1616
	s_waitcnt lgkmcnt(0)
	v_mfma_f32_32x32x16_bf16 v[48:63], v[88:91], v[64:67], v[48:63]
	ds_read_b64 v[88:89], v83 offset:96
	ds_read_b64 v[90:91], v83 offset:112
	v_cvt_pk_bf16_f32 v64, v101, v104
	v_cvt_pk_bf16_f32 v65, v115, v118
	v_cvt_pk_bf16_f32 v66, v122, v125
	v_cvt_pk_bf16_f32 v67, v171, v175
	s_waitcnt lgkmcnt(0)
	s_nop 0
	v_mfma_f32_32x32x16_bf16 v[0:15], v[88:91], v[64:67], v[0:15]
	ds_read_b64 v[88:89], v84 offset:608
	ds_read_b64 v[90:91], v84 offset:624
	s_waitcnt lgkmcnt(0)
	v_mfma_f32_32x32x16_bf16 v[16:31], v[88:91], v[64:67], v[16:31]
	ds_read_b64 v[88:89], v85 offset:1120
	ds_read_b64 v[90:91], v85 offset:1136
	s_waitcnt lgkmcnt(0)
	v_mfma_f32_32x32x16_bf16 v[32:47], v[88:91], v[64:67], v[32:47]
	ds_read_b64 v[88:89], v86 offset:1632
	ds_read_b64 v[90:91], v86 offset:1648
	s_waitcnt lgkmcnt(0)
	v_mfma_f32_32x32x16_bf16 v[48:63], v[88:91], v[64:67], v[48:63]
	ds_read_b64 v[88:89], v83 offset:128
	ds_read_b64 v[90:91], v83 offset:144
	v_cvt_pk_bf16_f32 v64, v99, v102
	v_cvt_pk_bf16_f32 v65, v105, v107
	v_cvt_pk_bf16_f32 v66, v109, v111
	v_cvt_pk_bf16_f32 v67, v126, v172
	s_waitcnt lgkmcnt(0)
	s_nop 0
	v_mfma_f32_32x32x16_bf16 v[0:15], v[88:91], v[64:67], v[0:15]
	ds_read_b64 v[88:89], v84 offset:640
	ds_read_b64 v[90:91], v84 offset:656
	s_waitcnt lgkmcnt(0)
	v_mfma_f32_32x32x16_bf16 v[16:31], v[88:91], v[64:67], v[16:31]
	ds_read_b64 v[88:89], v85 offset:1152
	ds_read_b64 v[90:91], v85 offset:1168
	s_waitcnt lgkmcnt(0)
; #define LAS __attribute__((address_space(3)))
; __device__ __forceinline__ unsigned cvtpk(float lo, float hi) { f32x2 v = {lo, hi}; bf16x2_t b = __builtin_convertvector(v, bf16x2_t); return __builtin_bit_cast(unsigned, b); }
; #define MFMA32(a, b, c) __builtin_amdgcn_mfma_f32_32x32x16_bf16((a), (b), (c), 0, 0, 0)
; template <bool CAUSAL>
; __device__ __forceinline__ void attn_tile(const LAS unsigned char* Ks, const LAS unsigned char* Vts, const bf16x8 (&qf)[8], int qi, int r32, int hi, f32x16 (&O)[4], float& m2, float& l) {
;     ...
;         for (int s = 0; s < 4; ++s)
; #pragma unroll
;             for (int r = 0; r < 16; ++r) { const float p = __builtin_amdgcn_exp2f(S[s][r] * c - mn); S[s][r] = p; lsum += p; }
; #pragma unroll
;         for (int s = 0; s < 4; ++s)
; #pragma unroll
;             for (int j = 0; j < 2; ++j) {
;                 u32x4 pw; pw.x = cvtpk(S[s][8 * j + 0], S[s][8 * j + 1]); pw.y = cvtpk(S[s][8 * j + 2], S[s][8 * j + 3]); pw.z = cvtpk(S[s][8 * j + 4], S[s][8 * j + 5]); pw.w = cvtpk(S[s][8 * j + 6], S[s][8 * j + 7]);
;                 const bf16x8 pf = __builtin_bit_cast(bf16x8, pw);
; #pragma unroll
;                 for (int d = 0; d < 4; ++d) {
;                     const LAS unsigned char* vp = Vts + (32 * d + r32) * VT_STRIDE + (128 * hf + 32 * s + 16 * j + 4 * hi) * 2;
;                     const s16x4 lo = *(const LAS s16x4*)vp, h4 = *(const LAS s16x4*)(vp + 16);
;                     const bf16x8 vf = __builtin_shufflevector(lo, h4, 0, 1, 2, 3, 4, 5, 6, 7);
;                     O[d] = MFMA32(vf, pf, O[d]);
;                 }
;                 __builtin_amdgcn_sched_barrier(0);
;             }
;     }
	v_mfma_f32_32x32x16_bf16 v[32:47], v[88:91], v[64:67], v[32:47]
	ds_read_b64 v[88:89], v86 offset:1664
	ds_read_b64 v[90:91], v86 offset:1680
	s_waitcnt lgkmcnt(0)
	v_mfma_f32_32x32x16_bf16 v[48:63], v[88:91], v[64:67], v[48:63]
	ds_read_b64 v[88:89], v83 offset:160
	ds_read_b64 v[90:91], v83 offset:176
	v_cvt_pk_bf16_f32 v64, v98, v100
	v_cvt_pk_bf16_f32 v65, v103, v106
	v_cvt_pk_bf16_f32 v66, v108, v110
	v_cvt_pk_bf16_f32 v67, v123, v127
	s_waitcnt lgkmcnt(0)
	s_nop 0
	v_mfma_f32_32x32x16_bf16 v[0:15], v[88:91], v[64:67], v[0:15]
	ds_read_b64 v[88:89], v84 offset:672
	ds_read_b64 v[90:91], v84 offset:688
	s_waitcnt lgkmcnt(0)
	v_mfma_f32_32x32x16_bf16 v[16:31], v[88:91], v[64:67], v[16:31]
	ds_read_b64 v[88:89], v85 offset:1184
	ds_read_b64 v[90:91], v85 offset:1200
	s_waitcnt lgkmcnt(0)
	v_mfma_f32_32x32x16_bf16 v[32:47], v[88:91], v[64:67], v[32:47]
	ds_read_b64 v[88:89], v86 offset:1696
	ds_read_b64 v[90:91], v86 offset:1712
	s_waitcnt lgkmcnt(0)
	v_mfma_f32_32x32x16_bf16 v[48:63], v[88:91], v[64:67], v[48:63]
	ds_read_b64 v[64:65], v83 offset:192
	ds_read_b64 v[66:67], v83 offset:208
	v_cvt_pk_bf16_f32 v88, v97, v68
	v_cvt_pk_bf16_f32 v89, v69, v70
	v_cvt_pk_bf16_f32 v90, v71, v72
	v_cvt_pk_bf16_f32 v91, v73, v74
	s_waitcnt lgkmcnt(0)
	s_nop 0
	v_mfma_f32_32x32x16_bf16 v[0:15], v[64:67], v[88:91], v[0:15]
	ds_read_b64 v[64:65], v84 offset:704
	ds_read_b64 v[66:67], v84 offset:720
	s_waitcnt lgkmcnt(0)
	v_mfma_f32_32x32x16_bf16 v[16:31], v[64:67], v[88:91], v[16:31]
	ds_read_b64 v[64:65], v85 offset:1216
	ds_read_b64 v[66:67], v85 offset:1232
	s_waitcnt lgkmcnt(0)
	v_mfma_f32_32x32x16_bf16 v[32:47], v[64:67], v[88:91], v[32:47]
	ds_read_b64 v[64:65], v86 offset:1728
	ds_read_b64 v[66:67], v86 offset:1744
	s_waitcnt lgkmcnt(0)
	v_mfma_f32_32x32x16_bf16 v[48:63], v[64:67], v[88:91], v[48:63]
	ds_read_b64 v[64:65], v83 offset:224
	ds_read_b64 v[66:67], v83 offset:240
	v_cvt_pk_bf16_f32 v88, v75, v76
	v_cvt_pk_bf16_f32 v89, v77, v78
	v_cvt_pk_bf16_f32 v90, v79, v80
	v_cvt_pk_bf16_f32 v91, v81, v82
	s_waitcnt lgkmcnt(0)
	s_nop 0
	v_mfma_f32_32x32x16_bf16 v[0:15], v[64:67], v[88:91], v[0:15]
	ds_read_b64 v[64:65], v84 offset:736
	ds_read_b64 v[66:67], v84 offset:752
	s_waitcnt lgkmcnt(0)
	v_mfma_f32_32x32x16_bf16 v[16:31], v[64:67], v[88:91], v[16:31]
	ds_read_b64 v[64:65], v85 offset:1248
	ds_read_b64 v[66:67], v85 offset:1264
	s_waitcnt lgkmcnt(0)
	v_mfma_f32_32x32x16_bf16 v[32:47], v[64:67], v[88:91], v[32:47]
	ds_read_b64 v[64:65], v86 offset:1760
	ds_read_b64 v[66:67], v86 offset:1776
	s_waitcnt lgkmcnt(0)
	v_mfma_f32_32x32x16_bf16 v[48:63], v[64:67], v[88:91], v[48:63]
	v_add_f32_e32 v64, v97, v96
	v_add_f32_e32 v64, v68, v64
	v_add_f32_e32 v64, v69, v64
	v_add_f32_e32 v64, v70, v64
	v_add_f32_e32 v64, v71, v64
	v_add_f32_e32 v64, v72, v64
	v_add_f32_e32 v64, v73, v64
	v_add_f32_e32 v64, v74, v64
	v_add_f32_e32 v64, v75, v64
	v_add_f32_e32 v64, v76, v64
	v_add_f32_e32 v64, v77, v64
	v_add_f32_e32 v64, v78, v64
	v_add_f32_e32 v64, v79, v64
	v_add_f32_e32 v64, v80, v64
	v_add_f32_e32 v64, v81, v64
	s_mov_b32 s25, 1
	s_and_b64 vcc, exec, s[0:1]
	v_mov_b32_e32 v169, v170
	s_mov_b64 s[0:1], 0
	v_add_f32_e32 v166, v82, v64
	s_cbranch_vccnz .LBB0_400
; __device__ __forceinline__ unsigned cvtpk(float lo, float hi) { f32x2 v = {lo, hi}; bf16x2_t b = __builtin_convertvector(v, bf16x2_t); return __builtin_bit_cast(unsigned, b); }
; __device__ __forceinline__ void store_orow(bf16_t* orow, const f32x16 (&O)[4], float sc, int hi, bool st) {
; #pragma unroll
;     for (int d = 0; d < 4; ++d)
; #pragma unroll
;         for (int k = 0; k < 2; ++k) {
;             const unsigned x0 = cvtpk(O[d][8 * k + 0] * sc, O[d][8 * k + 1] * sc), x1 = cvtpk(O[d][8 * k + 2] * sc, O[d][8 * k + 3] * sc);
;             const unsigned y0 = cvtpk(O[d][8 * k + 4] * sc, O[d][8 * k + 5] * sc), y1 = cvtpk(O[d][8 * k + 6] * sc, O[d][8 * k + 7] * sc);
;             const auto r0 = __builtin_amdgcn_permlane32_swap(x0, y0, false, false), r1 = __builtin_amdgcn_permlane32_swap(x1, y1, false, false);
;             u32x4 w; w.x = r0[0]; w.y = r1[0]; w.z = r0[1]; w.w = r1[1];
;             if (st) *(u32x4*)(orow + 32 * d + 16 * k + 8 * hi) = w;
;         }
; }
; __global__ void __launch_bounds__(512, 2) mk_fwd(Args a) {
;     ...
;                         attn_tile<false>(lds + LDS_KS, lds + LDS_VT, qf, 0, r32, hi, O, m2, ll);
;                         store_orow(MIX + (size_t)tok * DM + 1536 + 128 * hm, O, 1.0f / ll, hi, true);
;                         __syncthreads();
	ds_bpermute_b32 v64, v167, v166
	v_lshlrev_b32_e32 v128, 1, v164
	s_mov_b32 s25, s14
	s_waitcnt lgkmcnt(0)
	v_add_f32_e32 v66, v166, v64
	v_div_scale_f32 v67, s[0:1], v66, v66, 1.0
	v_rcp_f32_e32 v68, v67
	v_lshlrev_b64 v[64:65], 12, v[162:163]
	v_lshl_add_u64 v[64:65], s[10:11], 0, v[64:65]
	v_lshl_add_u64 v[64:65], s[74:75], 1, v[64:65]
	v_fma_f32 v69, -v67, v68, 1.0
	v_fmac_f32_e32 v68, v69, v68
	v_div_scale_f32 v69, vcc, 1.0, v66, 1.0
	v_mul_f32_e32 v70, v69, v68
	v_fma_f32 v71, -v67, v70, v69
	v_fmac_f32_e32 v70, v71, v68
	v_fma_f32 v67, -v67, v70, v69
	v_div_fmas_f32 v67, v67, v68, v70
	v_div_fixup_f32 v66, v67, v66, 1.0
	v_pk_mul_f32 v[0:1], v[0:1], v[66:67] op_sel_hi:[1,0]
	v_pk_mul_f32 v[2:3], v[2:3], v[66:67] op_sel_hi:[1,0]
	v_cvt_pk_bf16_f32 v0, v0, v1
	v_cvt_pk_bf16_f32 v1, v2, v3
	v_pk_mul_f32 v[2:3], v[4:5], v[66:67] op_sel_hi:[1,0]
	v_pk_mul_f32 v[4:5], v[6:7], v[66:67] op_sel_hi:[1,0]
	v_cvt_pk_bf16_f32 v2, v2, v3
	v_cvt_pk_bf16_f32 v3, v4, v5
	v_lshl_add_u64 v[64:65], v[64:65], 0, v[128:129]
	v_permlane32_swap_b32_e32 v0, v2
	v_permlane32_swap_b32_e32 v1, v3
	flat_store_dwordx4 v[64:65], v[0:3] offset:3072
	v_pk_mul_f32 v[4:5], v[14:15], v[66:67] op_sel_hi:[1,0]
	s_mov_b64 s[0:1], 0
	v_pk_mul_f32 v[0:1], v[8:9], v[66:67] op_sel_hi:[1,0]
	v_pk_mul_f32 v[2:3], v[10:11], v[66:67] op_sel_hi:[1,0]
	v_cvt_pk_bf16_f32 v0, v0, v1
	v_cvt_pk_bf16_f32 v1, v2, v3
	v_pk_mul_f32 v[2:3], v[12:13], v[66:67] op_sel_hi:[1,0]
	v_readlane_b32 s74, v254, 61
	v_cvt_pk_bf16_f32 v2, v2, v3
	v_cvt_pk_bf16_f32 v3, v4, v5
	s_nop 0
	v_permlane32_swap_b32_e32 v0, v2
	v_permlane32_swap_b32_e32 v1, v3
	flat_store_dwordx4 v[64:65], v[0:3] offset:3104
	v_pk_mul_f32 v[4:5], v[22:23], v[66:67] op_sel_hi:[1,0]
	s_nop 0
	v_pk_mul_f32 v[0:1], v[16:17], v[66:67] op_sel_hi:[1,0]
	v_pk_mul_f32 v[2:3], v[18:19], v[66:67] op_sel_hi:[1,0]
	v_cvt_pk_bf16_f32 v0, v0, v1
	v_cvt_pk_bf16_f32 v1, v2, v3
	v_pk_mul_f32 v[2:3], v[20:21], v[66:67] op_sel_hi:[1,0]
	s_nop 0
	v_cvt_pk_bf16_f32 v2, v2, v3
	v_cvt_pk_bf16_f32 v3, v4, v5
	s_nop 0
	v_permlane32_swap_b32_e32 v0, v2
	v_permlane32_swap_b32_e32 v1, v3
	flat_store_dwordx4 v[64:65], v[0:3] offset:3136
	v_pk_mul_f32 v[4:5], v[30:31], v[66:67] op_sel_hi:[1,0]
	s_nop 0
	v_pk_mul_f32 v[0:1], v[24:25], v[66:67] op_sel_hi:[1,0]
	v_pk_mul_f32 v[2:3], v[26:27], v[66:67] op_sel_hi:[1,0]
	v_cvt_pk_bf16_f32 v0, v0, v1
	v_cvt_pk_bf16_f32 v1, v2, v3
	v_pk_mul_f32 v[2:3], v[28:29], v[66:67] op_sel_hi:[1,0]
	s_nop 0
	v_cvt_pk_bf16_f32 v2, v2, v3
	v_cvt_pk_bf16_f32 v3, v4, v5
	s_nop 0
	v_permlane32_swap_b32_e32 v0, v2
	v_permlane32_swap_b32_e32 v1, v3
	flat_store_dwordx4 v[64:65], v[0:3] offset:3168
	v_pk_mul_f32 v[4:5], v[38:39], v[66:67] op_sel_hi:[1,0]
	s_nop 0
	v_pk_mul_f32 v[0:1], v[32:33], v[66:67] op_sel_hi:[1,0]
	v_pk_mul_f32 v[2:3], v[34:35], v[66:67] op_sel_hi:[1,0]
	v_cvt_pk_bf16_f32 v0, v0, v1
	v_cvt_pk_bf16_f32 v1, v2, v3
	v_pk_mul_f32 v[2:3], v[36:37], v[66:67] op_sel_hi:[1,0]
	s_nop 0
	v_cvt_pk_bf16_f32 v2, v2, v3
	v_cvt_pk_bf16_f32 v3, v4, v5
	s_nop 0
	v_permlane32_swap_b32_e32 v0, v2
	v_permlane32_swap_b32_e32 v1, v3
	flat_store_dwordx4 v[64:65], v[0:3] offset:3200
	v_pk_mul_f32 v[4:5], v[46:47], v[66:67] op_sel_hi:[1,0]
	s_nop 0
	v_pk_mul_f32 v[0:1], v[40:41], v[66:67] op_sel_hi:[1,0]
	v_pk_mul_f32 v[2:3], v[42:43], v[66:67] op_sel_hi:[1,0]
	v_cvt_pk_bf16_f32 v0, v0, v1
	v_cvt_pk_bf16_f32 v1, v2, v3
	v_pk_mul_f32 v[2:3], v[44:45], v[66:67] op_sel_hi:[1,0]
	s_nop 0
	v_cvt_pk_bf16_f32 v2, v2, v3
	v_cvt_pk_bf16_f32 v3, v4, v5
	s_nop 0
	v_permlane32_swap_b32_e32 v0, v2
	v_permlane32_swap_b32_e32 v1, v3
	flat_store_dwordx4 v[64:65], v[0:3] offset:3232
	v_pk_mul_f32 v[4:5], v[54:55], v[66:67] op_sel_hi:[1,0]
	s_nop 0
	v_pk_mul_f32 v[0:1], v[48:49], v[66:67] op_sel_hi:[1,0]
	v_pk_mul_f32 v[2:3], v[50:51], v[66:67] op_sel_hi:[1,0]
	v_cvt_pk_bf16_f32 v0, v0, v1
	v_cvt_pk_bf16_f32 v1, v2, v3
	v_pk_mul_f32 v[2:3], v[52:53], v[66:67] op_sel_hi:[1,0]
	s_nop 0
	v_cvt_pk_bf16_f32 v2, v2, v3
	v_cvt_pk_bf16_f32 v3, v4, v5
	s_nop 0
	v_permlane32_swap_b32_e32 v0, v2
	v_permlane32_swap_b32_e32 v1, v3
	flat_store_dwordx4 v[64:65], v[0:3] offset:3264
	v_pk_mul_f32 v[4:5], v[62:63], v[66:67] op_sel_hi:[1,0]
	s_nop 0
	v_pk_mul_f32 v[0:1], v[56:57], v[66:67] op_sel_hi:[1,0]
	v_pk_mul_f32 v[2:3], v[58:59], v[66:67] op_sel_hi:[1,0]
	v_cvt_pk_bf16_f32 v0, v0, v1
	v_cvt_pk_bf16_f32 v1, v2, v3
	v_pk_mul_f32 v[2:3], v[60:61], v[66:67] op_sel_hi:[1,0]
	s_nop 0
	v_cvt_pk_bf16_f32 v2, v2, v3
	v_cvt_pk_bf16_f32 v3, v4, v5
	s_nop 0
	v_permlane32_swap_b32_e32 v0, v2
	v_permlane32_swap_b32_e32 v1, v3
	flat_store_dwordx4 v[64:65], v[0:3] offset:3296
	s_waitcnt lgkmcnt(0)
	s_barrier
